# in-projection q/k epilogue: result stores issued behind the next block's rope loads (own registers); gating units start at bx^128 so workgroups with a context attention unit take eight gating units
# baseline (speedup 1.0000x reference)
; __device__ __forceinline__ int tid_fresh() { int t = threadIdx.x; asm volatile("" : "+v"(t)); return t; }
; __device__ __forceinline__ void gate_phase(int bx, int G, bool skip_ctx, const bf16* __restrict__ VG, const bf16* __restrict__ U, const float* __restrict__ stats, ...
;     const int tid = tid_fresh(), wid = tid >> 6, lane = tid & 63, r32 = lane & 31, hi = lane >> 5;
;     bf16* T = (bf16*)lds;
;     const int q = tid >> 2, dc = (tid & 3) * 16;
;     const int db = wid & 1, pb = wid >> 1, p = pb * 32 + r32;
;     const int NU = (M / 128) * 8;
;     auto unit_ok = [&](int u) { return u < NU && !(skip_ctx && ((u >> 3) % 34) < 2); };
;     auto next_unit = [&](int u) { u += G; while (u < NU && !unit_ok(u)) u += G; return u; };
;     int u = bx; if (!unit_ok(u)) u = next_unit(u);
; __global__ void __launch_bounds__(NTHR, 2) fwd_kernel(Args A_) {
;     ...
;                     gate_phase(bx, G, lastl, VGb, Ub, statp, A->g_sg + l * 512, A->b_sg + l * 512, (const bf16*)(ws + WS_WS) + (size_t)l * 8 * 128 * 128, A->b_s + l * 8 * 128, MIXb, (char*)lds);
.LBB0_38:
	s_load_dwordx4 s[8:11], s[0:1], 0x68
	s_load_dwordx2 s[6:7], s[0:1], 0x80
	v_readlane_b32 s22, v254, 10
	v_readlane_b32 s23, v254, 11
	v_readlane_b32 s26, v254, 8
	s_and_b64 s[22:23], s[22:23], s[20:21]
	v_readlane_b32 s27, v254, 9
	s_or_b64 s[22:23], s[26:27], s[22:23]
	v_mov_b32_e32 v4, v171
	s_andn2_b64 vcc, exec, s[22:23]
	s_mov_b32 s3, s2
	s_and_b64 s[26:27], s[20:21], exec
	s_cselect_b32 s27, 0, 0x80
	s_cmp_eq_u32 s24, 0x100
	s_cselect_b32 s27, s27, 0
	s_xor_b32 s3, s2, s27
	v_readlane_b32 s13, v254, 49
	s_cbranch_vccz .LBB0_42

; __device__ __forceinline__ unsigned pk2(float lo, float hi) { return pg8::cvt_pk_bf16(lo, hi); }
;     __device__ __forceinline__ void operator()(const f32x4 (&acc)[2][2][4][2], const pg8::Unit& u, int wr, int wc, int fr, int fq) const {
;     ...
;                         u32x4 w; w.x = pk2(y0[0], y0[1]); w.y = pk2(y0[2], y0[3]); w.z = pk2(y1[0], y1[1]); w.w = pk2(y1[2], y1[3]);
;                         *(u32x4*)(dst + (size_t)row * pitch + hcol + 32 * bj + 8 * fq) = w;
.Lqk_st_0:
	global_store_dwordx4 v[252:253], v[248:251], off
	s_branch .LBB0_237
.Lqk_st_1:
	global_store_dwordx4 v[252:253], v[248:251], off offset:64
	s_branch .LBB0_243

; __device__ __forceinline__ unsigned pk2(float lo, float hi) { return pg8::cvt_pk_bf16(lo, hi); }
;     __device__ __forceinline__ void operator()(const f32x4 (&acc)[2][2][4][2], const pg8::Unit& u, int wr, int wc, int fr, int fq) const {
;     ...
;                 for (int m = 0; m < 4; ++m) {
;                     const int rl = ai * 128 + wr * 64 + m * 16 + fr;
;                     const int row = pm * 256 + rl;
;                     float ss = 0.f;
; #pragma unroll
;                     for (int bj = 0; bj < 2; ++bj)
; #pragma unroll
;                         for (int n = 0; n < 2; ++n) { const f32x4 v = acc[ai][bj][m][n]; ss += (v[0] * v[0] + v[1] * v[1]) + (v[2] * v[2] + v[3] * v[3]); }
;                     ss = sum_fq(ss);
;                     const float rstd = __builtin_amdgcn_rsqf(ss * (1.0f / 64.0f) + EPS);
;                     const int sp = seq0 + rl;
; #pragma unroll
;                     for (int bj = 0; bj < 2; ++bj) {
;                         f32x4 y0 = acc[ai][bj][m][0] * (rstd * qscale) * gv[bj][0], y1 = acc[ai][bj][m][1] * (rstd * qscale) * gv[bj][1];
;                         if (!isctx) {
;                             const int pos = bj == 0 ? (sp >> 6) : (sp & 63);
;                             const f32x4 c0 = *(const f32x4*)(ropec + pos * 16 + fbase), c1 = *(const f32x4*)(ropec + pos * 16 + fbase + 4);
;                             const f32x4 s0 = *(const f32x4*)(ropes + pos * 16 + fbase), s1 = *(const f32x4*)(ropes + pos * 16 + fbase + 4);
;                             f32x4 p0, p1;
; #pragma unroll
;                             for (int j = 0; j < 4; ++j) { p0[j] = xor32(y0[j], lowhalf); p1[j] = xor32(y1[j], lowhalf); }
;                             if (lowhalf) { y0 = y0 * c0 - p0 * s0; y1 = y1 * c1 - p1 * s1; }
;                             else         { y0 = p0 * s0 + y0 * c0; y1 = p1 * s1 + y1 * c1; }
;                         }
;                         u32x4 w; w.x = pk2(y0[0], y0[1]); w.y = pk2(y0[2], y0[3]); w.z = pk2(y1[0], y1[1]); w.w = pk2(y1[2], y1[3]);
;                         *(u32x4*)(dst + (size_t)row * pitch + hcol + 32 * bj + 8 * fq) = w;
.LBB0_231:
	s_lshl_b32 s22, s94, 8
	s_and_b64 s[20:21], s[16:17], exec
	s_cselect_b32 s20, 0, s22
	s_or_b32 s20, s20, s81
	s_and_b64 s[22:23], s[16:17], exec
	s_mov_b32 s21, 0x10dfa000
	s_cselect_b32 s21, s21, 0xebfa000
	s_lshl_b32 s26, s72, 8
	s_add_u32 s22, s28, s21
	s_addc_u32 s23, s29, 0
	s_and_b64 s[16:17], s[16:17], exec
	s_cselect_b32 s27, 7, 9
	s_ashr_i32 s21, s20, 31
	s_lshl_b64 s[16:17], s[20:21], 1
	s_add_u32 s16, s22, s16
	v_add_u32_e32 v144, s26, v217
	s_addc_u32 s17, s23, s17
	v_lshlrev_b32_e32 v160, 1, v170
	v_ashrrev_i32_e32 v145, 31, v144
	v_lshl_add_u64 v[184:185], s[16:17], 0, v[160:161]
	v_lshlrev_b64 v[144:145], s27, v[144:145]
	v_lshl_add_u64 v[192:193], v[144:145], 1, v[184:185]
	v_cvt_pk_bf16_f32 v248, v196, v197
	v_cvt_pk_bf16_f32 v249, v190, v191
	v_cvt_pk_bf16_f32 v250, v194, v195
	v_cvt_pk_bf16_f32 v251, v188, v189
	v_mov_b64_e32 v[252:253], v[192:193]
	v_mov_b32_e32 v187, v186
	v_pk_mul_f32 v[148:149], v[116:117], v[186:187]
	v_mov_b32_e32 v144, v186
	v_mov_b32_e32 v145, v186
	v_pk_mul_f32 v[146:147], v[118:119], v[144:145]
	v_pk_mul_f32 v[144:145], v[110:111], v[144:145]
	v_pk_mul_f32 v[188:189], v[134:135], v[146:147]
	v_pk_mul_f32 v[146:147], v[108:109], v[186:187]
	v_pk_mul_f32 v[190:191], v[132:133], v[148:149]
	v_pk_mul_f32 v[186:187], v[128:129], v[146:147]
	v_cndmask_b32_e64 v146, 0, 1, s[6:7]
	v_cmp_ne_u32_e64 s[16:17], 1, v146
	s_andn2_b64 vcc, exec, s[6:7]
	v_pk_mul_f32 v[194:195], v[130:131], v[144:145]
	s_cbranch_vccnz .Lqk_st_0
	global_load_dwordx4 v[144:147], v[176:177], off offset:16
	global_load_dwordx4 v[152:155], v[176:177], off
	global_load_dwordx4 v[148:151], v[178:179], off offset:16
	global_load_dwordx4 v[156:159], v[178:179], off
	global_store_dwordx4 v[252:253], v[248:251], off
	v_mov_b32_e32 v160, v190
	v_mov_b32_e32 v196, v190
	s_nop 1
	v_permlane32_swap_b32_e32 v160, v196
	v_cndmask_b32_e64 v228, v160, v196, s[8:9]
	v_mov_b32_e32 v160, v186
	v_mov_b32_e32 v196, v186
	s_nop 1
	v_permlane32_swap_b32_e32 v160, v196
	v_cndmask_b32_e64 v230, v160, v196, s[8:9]
	v_mov_b32_e32 v160, v191
	v_mov_b32_e32 v196, v191
	s_nop 1
	v_permlane32_swap_b32_e32 v160, v196
	v_cndmask_b32_e64 v229, v160, v196, s[8:9]
	v_mov_b32_e32 v160, v187
	v_mov_b32_e32 v196, v187
	s_nop 1
	v_permlane32_swap_b32_e32 v160, v196
	v_cndmask_b32_e64 v231, v160, v196, s[8:9]
	v_mov_b32_e32 v160, v188
	v_mov_b32_e32 v196, v188
	s_nop 1
	v_permlane32_swap_b32_e32 v160, v196
	v_cndmask_b32_e64 v198, v160, v196, s[8:9]
	v_mov_b32_e32 v160, v194
	v_mov_b32_e32 v196, v194
	s_nop 1
	v_permlane32_swap_b32_e32 v160, v196
	v_cndmask_b32_e64 v196, v160, v196, s[8:9]
	v_mov_b32_e32 v160, v189
	v_mov_b32_e32 v197, v189
	s_nop 1
	v_permlane32_swap_b32_e32 v160, v197
	v_cndmask_b32_e64 v199, v160, v197, s[8:9]
	v_mov_b32_e32 v160, v195
	v_mov_b32_e32 v197, v195
	s_nop 1
	v_permlane32_swap_b32_e32 v160, v197
	v_cndmask_b32_e64 v197, v160, v197, s[8:9]
	s_waitcnt vmcnt(2)
	v_pk_mul_f32 v[148:149], v[148:149], v[230:231]
	s_waitcnt vmcnt(1)
	v_pk_mul_f32 v[156:157], v[156:157], v[228:229]
	s_and_saveexec_b64 s[6:7], s[10:11]
	s_xor_b64 s[6:7], exec, s[6:7]
	v_pk_mul_f32 v[158:159], v[158:159], v[198:199]
	v_pk_mul_f32 v[150:151], v[150:151], v[196:197]
	v_pk_fma_f32 v[188:189], v[188:189], v[154:155], v[158:159]
	v_pk_fma_f32 v[190:191], v[190:191], v[152:153], v[156:157]
	v_pk_fma_f32 v[194:195], v[194:195], v[146:147], v[150:151]
	v_pk_fma_f32 v[186:187], v[186:187], v[144:145], v[148:149]
	s_andn2_saveexec_b64 s[6:7], s[6:7]
	v_pk_mul_f32 v[158:159], v[158:159], v[198:199]
	v_pk_mul_f32 v[150:151], v[150:151], v[196:197]
	v_pk_fma_f32 v[188:189], v[188:189], v[154:155], v[158:159] neg_lo:[0,0,1] neg_hi:[0,0,1]
	v_pk_fma_f32 v[190:191], v[190:191], v[152:153], v[156:157] neg_lo:[0,0,1] neg_hi:[0,0,1]
	v_pk_fma_f32 v[194:195], v[194:195], v[146:147], v[150:151] neg_lo:[0,0,1] neg_hi:[0,0,1]
	v_pk_fma_f32 v[186:187], v[186:187], v[144:145], v[148:149] neg_lo:[0,0,1] neg_hi:[0,0,1]
	s_or_b64 exec, exec, s[6:7]
.LBB0_237:
	v_cvt_pk_bf16_f32 v248, v190, v191
	v_cvt_pk_bf16_f32 v249, v188, v189
	v_cvt_pk_bf16_f32 v250, v186, v187
	v_cvt_pk_bf16_f32 v251, v194, v195
	v_mov_b64_e32 v[252:253], v[192:193]
	s_and_b64 vcc, exec, s[16:17]
	s_nop 0
	v_mul_f32_e32 v144, v113, v113
	v_mul_f32_e32 v145, v115, v115
	v_fmac_f32_e32 v144, v112, v112
	v_fmac_f32_e32 v145, v114, v114
	v_add_f32_e32 v144, v144, v145
	v_mul_f32_e32 v145, v105, v105
	v_mul_f32_e32 v146, v107, v107
	v_fmac_f32_e32 v145, v104, v104
	v_fmac_f32_e32 v146, v106, v106
	v_add_f32_e32 v145, v145, v146
	v_add_f32_e32 v144, v144, v145
	v_mul_f32_e32 v145, v101, v101
	v_mul_f32_e32 v146, v103, v103
	v_fmac_f32_e32 v145, v100, v100
	v_fmac_f32_e32 v146, v102, v102
	v_add_f32_e32 v145, v145, v146
	v_add_f32_e32 v144, v144, v145
	v_mul_f32_e32 v145, v93, v93
	v_mul_f32_e32 v146, v95, v95
	v_fmac_f32_e32 v145, v92, v92
	v_fmac_f32_e32 v146, v94, v94
	v_add_f32_e32 v145, v145, v146
	v_add_f32_e32 v144, v144, v145
	v_mov_b32_e32 v145, v144
	s_nop 1
	v_permlane16_swap_b32_e32 v144, v145
	v_add_f32_e32 v144, v144, v145
	v_mov_b32_e32 v145, v144
	s_nop 1
	v_permlane32_swap_b32_e32 v144, v145
	v_add_f32_e32 v144, v144, v145
	v_fmamk_f32 v144, v144, 0x3c800000, v200
	v_rsq_f32_e32 v144, v144
	s_nop 0
	v_mul_f32_e32 v186, v227, v144
	v_pk_mul_f32 v[144:145], v[112:113], v[186:187] op_sel_hi:[1,0]
	v_pk_mul_f32 v[146:147], v[114:115], v[186:187] op_sel_hi:[1,0]
	v_pk_mul_f32 v[192:193], v[140:141], v[144:145]
	v_pk_mul_f32 v[190:191], v[142:143], v[146:147]
	v_pk_mul_f32 v[144:145], v[104:105], v[186:187] op_sel_hi:[1,0]
	v_pk_mul_f32 v[146:147], v[106:107], v[186:187] op_sel_hi:[1,0]
	v_pk_mul_f32 v[196:197], v[136:137], v[144:145]
	v_pk_mul_f32 v[194:195], v[138:139], v[146:147]
	s_cbranch_vccnz .Lqk_st_1
; __device__ __forceinline__ unsigned pk2(float lo, float hi) { return pg8::cvt_pk_bf16(lo, hi); }
;     __device__ __forceinline__ void operator()(const f32x4 (&acc)[2][2][4][2], const pg8::Unit& u, int wr, int wc, int fr, int fq) const {
;     ...
;                     const int sp = seq0 + rl;
; #pragma unroll
;                     for (int bj = 0; bj < 2; ++bj) {
;                         f32x4 y0 = acc[ai][bj][m][0] * (rstd * qscale) * gv[bj][0], y1 = acc[ai][bj][m][1] * (rstd * qscale) * gv[bj][1];
;                         if (!isctx) {
;                             const int pos = bj == 0 ? (sp >> 6) : (sp & 63);
;                             const f32x4 c0 = *(const f32x4*)(ropec + pos * 16 + fbase), c1 = *(const f32x4*)(ropec + pos * 16 + fbase + 4);
;                             const f32x4 s0 = *(const f32x4*)(ropes + pos * 16 + fbase), s1 = *(const f32x4*)(ropes + pos * 16 + fbase + 4);
;                             f32x4 p0, p1;
; #pragma unroll
;                             for (int j = 0; j < 4; ++j) { p0[j] = xor32(y0[j], lowhalf); p1[j] = xor32(y1[j], lowhalf); }
;                             if (lowhalf) { y0 = y0 * c0 - p0 * s0; y1 = y1 * c1 - p1 * s1; }
;                             else         { y0 = p0 * s0 + y0 * c0; y1 = p1 * s1 + y1 * c1; }
;                         }
;                         u32x4 w; w.x = pk2(y0[0], y0[1]); w.y = pk2(y0[2], y0[3]); w.z = pk2(y1[0], y1[1]); w.w = pk2(y1[2], y1[3]);
;                         *(u32x4*)(dst + (size_t)row * pitch + hcol + 32 * bj + 8 * fq) = w;
	v_add_u32_e32 v144, s5, v219
	v_ashrrev_i32_e32 v144, 2, v144
	v_and_b32_e32 v144, -16, v144
	v_ashrrev_i32_e32 v145, 31, v144
	v_lshlrev_b64 v[148:149], 2, v[144:145]
	v_lshl_add_u64 v[150:151], v[172:173], 0, v[148:149]
	v_lshl_add_u64 v[156:157], v[174:175], 0, v[148:149]
	global_load_dwordx4 v[144:147], v[150:151], off offset:16
	global_load_dwordx4 v[152:155], v[150:151], off
	s_nop 0
	global_load_dwordx4 v[148:151], v[156:157], off offset:16
	s_nop 0
	global_load_dwordx4 v[156:159], v[156:157], off
	global_store_dwordx4 v[252:253], v[248:251], off offset:64
	v_mov_b32_e32 v160, v192
	v_mov_b32_e32 v187, v192
	s_nop 1
	v_permlane32_swap_b32_e32 v160, v187
	v_cndmask_b32_e64 v228, v160, v187, s[8:9]
	v_mov_b32_e32 v160, v196
	v_mov_b32_e32 v187, v196
	s_nop 1
	v_permlane32_swap_b32_e32 v160, v187
	v_cndmask_b32_e64 v230, v160, v187, s[8:9]
	v_mov_b32_e32 v160, v193
	v_mov_b32_e32 v187, v193
	s_nop 1
	v_permlane32_swap_b32_e32 v160, v187
	v_cndmask_b32_e64 v229, v160, v187, s[8:9]
	v_mov_b32_e32 v160, v197
	v_mov_b32_e32 v187, v197
	s_nop 1
	v_permlane32_swap_b32_e32 v160, v187
	v_cndmask_b32_e64 v231, v160, v187, s[8:9]
	v_mov_b32_e32 v160, v190
	v_mov_b32_e32 v187, v190
	s_nop 1
	v_permlane32_swap_b32_e32 v160, v187
	v_cndmask_b32_e64 v198, v160, v187, s[8:9]
	v_mov_b32_e32 v160, v194
	v_mov_b32_e32 v187, v194
	s_nop 1
	v_permlane32_swap_b32_e32 v160, v187
	v_cndmask_b32_e64 v188, v160, v187, s[8:9]
	v_mov_b32_e32 v160, v191
	v_mov_b32_e32 v187, v191
	s_nop 1
	v_permlane32_swap_b32_e32 v160, v187
	v_cndmask_b32_e64 v199, v160, v187, s[8:9]
	v_mov_b32_e32 v160, v195
	v_mov_b32_e32 v187, v195
	s_nop 1
	v_permlane32_swap_b32_e32 v160, v187
	v_cndmask_b32_e64 v189, v160, v187, s[8:9]
	s_waitcnt vmcnt(2)
	v_pk_mul_f32 v[148:149], v[148:149], v[230:231]
	s_waitcnt vmcnt(1)
	v_pk_mul_f32 v[156:157], v[156:157], v[228:229]
	s_and_saveexec_b64 s[6:7], s[10:11]
	s_xor_b64 s[6:7], exec, s[6:7]
	v_pk_mul_f32 v[158:159], v[158:159], v[198:199]
	v_pk_mul_f32 v[150:151], v[150:151], v[188:189]
	v_pk_fma_f32 v[190:191], v[190:191], v[154:155], v[158:159]
	v_pk_fma_f32 v[192:193], v[192:193], v[152:153], v[156:157]
	v_pk_fma_f32 v[194:195], v[194:195], v[146:147], v[150:151]
	v_pk_fma_f32 v[196:197], v[196:197], v[144:145], v[148:149]
	s_andn2_saveexec_b64 s[6:7], s[6:7]
	v_pk_mul_f32 v[158:159], v[158:159], v[198:199]
	v_pk_mul_f32 v[150:151], v[150:151], v[188:189]
	v_pk_fma_f32 v[190:191], v[190:191], v[154:155], v[158:159] neg_lo:[0,0,1] neg_hi:[0,0,1]
	v_pk_fma_f32 v[192:193], v[192:193], v[152:153], v[156:157] neg_lo:[0,0,1] neg_hi:[0,0,1]
	v_pk_fma_f32 v[194:195], v[194:195], v[146:147], v[150:151] neg_lo:[0,0,1] neg_hi:[0,0,1]
	v_pk_fma_f32 v[196:197], v[196:197], v[144:145], v[148:149] neg_lo:[0,0,1] neg_hi:[0,0,1]
	s_or_b64 exec, exec, s[6:7]
.LBB0_243:
	v_add_u32_e32 v144, s26, v219
	v_ashrrev_i32_e32 v145, 31, v144
	v_lshlrev_b64 v[144:145], s27, v[144:145]
	v_lshl_add_u64 v[188:189], v[144:145], 1, v[184:185]
	v_cvt_pk_bf16_f32 v248, v192, v193
	v_cvt_pk_bf16_f32 v249, v190, v191
	v_cvt_pk_bf16_f32 v250, v196, v197
	v_cvt_pk_bf16_f32 v251, v194, v195
	v_mov_b64_e32 v[252:253], v[188:189]
	v_mov_b32_e32 v187, v186
	v_pk_mul_f32 v[148:149], v[100:101], v[186:187]
	v_mov_b32_e32 v144, v186
	v_mov_b32_e32 v145, v186
	v_pk_mul_f32 v[146:147], v[102:103], v[144:145]
	v_pk_mul_f32 v[144:145], v[94:95], v[144:145]
	v_pk_mul_f32 v[190:191], v[134:135], v[146:147]
	v_pk_mul_f32 v[146:147], v[92:93], v[186:187]
	v_pk_mul_f32 v[192:193], v[132:133], v[148:149]
	v_pk_mul_f32 v[186:187], v[130:131], v[144:145]
	s_and_b64 vcc, exec, s[16:17]
	v_pk_mul_f32 v[194:195], v[128:129], v[146:147]
	s_cbranch_vccnz .Lqk_st_2
	global_load_dwordx4 v[144:147], v[176:177], off offset:1040
	global_load_dwordx4 v[152:155], v[176:177], off offset:1024
	global_load_dwordx4 v[148:151], v[178:179], off offset:1040
	global_load_dwordx4 v[156:159], v[178:179], off offset:1024
	global_store_dwordx4 v[252:253], v[248:251], off
	v_mov_b32_e32 v160, v192
	v_mov_b32_e32 v196, v192
	s_nop 1
	v_permlane32_swap_b32_e32 v160, v196
	v_cndmask_b32_e64 v228, v160, v196, s[8:9]
	v_mov_b32_e32 v160, v194
	v_mov_b32_e32 v196, v194
	s_nop 1
	v_permlane32_swap_b32_e32 v160, v196
	v_cndmask_b32_e64 v230, v160, v196, s[8:9]
	v_mov_b32_e32 v160, v193
	v_mov_b32_e32 v196, v193
	s_nop 1
	v_permlane32_swap_b32_e32 v160, v196
	v_cndmask_b32_e64 v229, v160, v196, s[8:9]
	v_mov_b32_e32 v160, v195
	v_mov_b32_e32 v196, v195
	s_nop 1
	v_permlane32_swap_b32_e32 v160, v196
	v_cndmask_b32_e64 v231, v160, v196, s[8:9]
	v_mov_b32_e32 v160, v190
	v_mov_b32_e32 v196, v190
	s_nop 1
	v_permlane32_swap_b32_e32 v160, v196
	v_cndmask_b32_e64 v198, v160, v196, s[8:9]
	v_mov_b32_e32 v160, v186
	v_mov_b32_e32 v196, v186
	s_nop 1
	v_permlane32_swap_b32_e32 v160, v196
	v_cndmask_b32_e64 v196, v160, v196, s[8:9]
	v_mov_b32_e32 v160, v191
	v_mov_b32_e32 v197, v191
	s_nop 1
	v_permlane32_swap_b32_e32 v160, v197
	v_cndmask_b32_e64 v199, v160, v197, s[8:9]
	v_mov_b32_e32 v160, v187
	v_mov_b32_e32 v197, v187
	s_nop 1
	v_permlane32_swap_b32_e32 v160, v197
	v_cndmask_b32_e64 v197, v160, v197, s[8:9]
	s_waitcnt vmcnt(2)
	v_pk_mul_f32 v[148:149], v[148:149], v[230:231]
	s_waitcnt vmcnt(1)
	v_pk_mul_f32 v[156:157], v[156:157], v[228:229]
	s_and_saveexec_b64 s[6:7], s[10:11]
	s_xor_b64 s[6:7], exec, s[6:7]
	v_pk_mul_f32 v[158:159], v[158:159], v[198:199]
	v_pk_mul_f32 v[150:151], v[150:151], v[196:197]
	v_pk_fma_f32 v[190:191], v[190:191], v[154:155], v[158:159]
	v_pk_fma_f32 v[192:193], v[192:193], v[152:153], v[156:157]
	v_pk_fma_f32 v[186:187], v[186:187], v[146:147], v[150:151]
	v_pk_fma_f32 v[194:195], v[194:195], v[144:145], v[148:149]
	s_andn2_saveexec_b64 s[6:7], s[6:7]
	v_pk_mul_f32 v[158:159], v[158:159], v[198:199]
	v_pk_mul_f32 v[150:151], v[150:151], v[196:197]
	v_pk_fma_f32 v[190:191], v[190:191], v[154:155], v[158:159] neg_lo:[0,0,1] neg_hi:[0,0,1]
	v_pk_fma_f32 v[192:193], v[192:193], v[152:153], v[156:157] neg_lo:[0,0,1] neg_hi:[0,0,1]
	v_pk_fma_f32 v[186:187], v[186:187], v[146:147], v[150:151] neg_lo:[0,0,1] neg_hi:[0,0,1]
	v_pk_fma_f32 v[194:195], v[194:195], v[144:145], v[148:149] neg_lo:[0,0,1] neg_hi:[0,0,1]
	s_or_b64 exec, exec, s[6:7]
; __device__ __forceinline__ unsigned pk2(float lo, float hi) { return pg8::cvt_pk_bf16(lo, hi); }
;     __device__ __forceinline__ void operator()(const f32x4 (&acc)[2][2][4][2], const pg8::Unit& u, int wr, int wc, int fr, int fq) const {
;     ...
;                 for (int m = 0; m < 4; ++m) {
;                     const int rl = ai * 128 + wr * 64 + m * 16 + fr;
;                     const int row = pm * 256 + rl;
;                     float ss = 0.f;
; #pragma unroll
;                     for (int bj = 0; bj < 2; ++bj)
; #pragma unroll
;                         for (int n = 0; n < 2; ++n) { const f32x4 v = acc[ai][bj][m][n]; ss += (v[0] * v[0] + v[1] * v[1]) + (v[2] * v[2] + v[3] * v[3]); }
;                     ss = sum_fq(ss);
;                     const float rstd = __builtin_amdgcn_rsqf(ss * (1.0f / 64.0f) + EPS);
;                     const int sp = seq0 + rl;
; #pragma unroll
;                     for (int bj = 0; bj < 2; ++bj) {
;                         f32x4 y0 = acc[ai][bj][m][0] * (rstd * qscale) * gv[bj][0], y1 = acc[ai][bj][m][1] * (rstd * qscale) * gv[bj][1];
;                         if (!isctx) {
;                             const int pos = bj == 0 ? (sp >> 6) : (sp & 63);
;                             const f32x4 c0 = *(const f32x4*)(ropec + pos * 16 + fbase), c1 = *(const f32x4*)(ropec + pos * 16 + fbase + 4);
;                             const f32x4 s0 = *(const f32x4*)(ropes + pos * 16 + fbase), s1 = *(const f32x4*)(ropes + pos * 16 + fbase + 4);
;                             f32x4 p0, p1;
; #pragma unroll
;                             for (int j = 0; j < 4; ++j) { p0[j] = xor32(y0[j], lowhalf); p1[j] = xor32(y1[j], lowhalf); }
;                             if (lowhalf) { y0 = y0 * c0 - p0 * s0; y1 = y1 * c1 - p1 * s1; }
;                             else         { y0 = p0 * s0 + y0 * c0; y1 = p1 * s1 + y1 * c1; }
;                         }
;                         u32x4 w; w.x = pk2(y0[0], y0[1]); w.y = pk2(y0[2], y0[3]); w.z = pk2(y1[0], y1[1]); w.w = pk2(y1[2], y1[3]);
;                         *(u32x4*)(dst + (size_t)row * pitch + hcol + 32 * bj + 8 * fq) = w;
.LBB0_249:
	v_cvt_pk_bf16_f32 v248, v192, v193
	v_cvt_pk_bf16_f32 v249, v190, v191
	v_cvt_pk_bf16_f32 v250, v194, v195
	v_cvt_pk_bf16_f32 v251, v186, v187
	v_mov_b64_e32 v[252:253], v[188:189]
	s_and_b64 vcc, exec, s[16:17]
	s_nop 0
	v_mul_f32_e32 v144, v97, v97
	v_mul_f32_e32 v145, v99, v99
	v_fmac_f32_e32 v144, v96, v96
	v_fmac_f32_e32 v145, v98, v98
	v_add_f32_e32 v144, v144, v145
	v_mul_f32_e32 v145, v89, v89
	v_mul_f32_e32 v146, v91, v91
	v_fmac_f32_e32 v145, v88, v88
	v_fmac_f32_e32 v146, v90, v90
	v_add_f32_e32 v145, v145, v146
	v_add_f32_e32 v144, v144, v145
	v_mul_f32_e32 v145, v85, v85
	v_mul_f32_e32 v146, v87, v87
	v_fmac_f32_e32 v145, v84, v84
	v_fmac_f32_e32 v146, v86, v86
	v_add_f32_e32 v145, v145, v146
	v_add_f32_e32 v144, v144, v145
	v_mul_f32_e32 v145, v77, v77
	v_mul_f32_e32 v146, v79, v79
	v_fmac_f32_e32 v145, v76, v76
	v_fmac_f32_e32 v146, v78, v78
	v_add_f32_e32 v145, v145, v146
	v_add_f32_e32 v144, v144, v145
	v_mov_b32_e32 v145, v144
	s_nop 1
	v_permlane16_swap_b32_e32 v144, v145
	v_add_f32_e32 v144, v144, v145
	v_mov_b32_e32 v145, v144
	s_nop 1
	v_permlane32_swap_b32_e32 v144, v145
	v_add_f32_e32 v144, v144, v145
	v_fmamk_f32 v144, v144, 0x3c800000, v200
	v_rsq_f32_e32 v144, v144
	s_nop 0
	v_mul_f32_e32 v186, v227, v144
	v_pk_mul_f32 v[144:145], v[96:97], v[186:187] op_sel_hi:[1,0]
	v_pk_mul_f32 v[146:147], v[98:99], v[186:187] op_sel_hi:[1,0]
	v_pk_mul_f32 v[192:193], v[140:141], v[144:145]
	v_pk_mul_f32 v[190:191], v[142:143], v[146:147]
	v_pk_mul_f32 v[144:145], v[88:89], v[186:187] op_sel_hi:[1,0]
	v_pk_mul_f32 v[146:147], v[90:91], v[186:187] op_sel_hi:[1,0]
	v_pk_mul_f32 v[196:197], v[136:137], v[144:145]
	v_pk_mul_f32 v[194:195], v[138:139], v[146:147]
	s_cbranch_vccnz .Lqk_st_3
	v_add_u32_e32 v144, s5, v220
	v_ashrrev_i32_e32 v144, 2, v144
	v_and_b32_e32 v144, -16, v144
	v_ashrrev_i32_e32 v145, 31, v144
	v_lshlrev_b64 v[148:149], 2, v[144:145]
	v_lshl_add_u64 v[150:151], v[172:173], 0, v[148:149]
	v_lshl_add_u64 v[156:157], v[174:175], 0, v[148:149]
	global_load_dwordx4 v[144:147], v[150:151], off offset:16
	global_load_dwordx4 v[152:155], v[150:151], off
	s_nop 0
	global_load_dwordx4 v[148:151], v[156:157], off offset:16
	s_nop 0
	global_load_dwordx4 v[156:159], v[156:157], off
	global_store_dwordx4 v[252:253], v[248:251], off offset:64
	v_mov_b32_e32 v160, v192
	v_mov_b32_e32 v187, v192
	s_nop 1
	v_permlane32_swap_b32_e32 v160, v187
	v_cndmask_b32_e64 v228, v160, v187, s[8:9]
	v_mov_b32_e32 v160, v196
	v_mov_b32_e32 v187, v196
	s_nop 1
	v_permlane32_swap_b32_e32 v160, v187
	v_cndmask_b32_e64 v230, v160, v187, s[8:9]
	v_mov_b32_e32 v160, v193
	v_mov_b32_e32 v187, v193
	s_nop 1
	v_permlane32_swap_b32_e32 v160, v187
	v_cndmask_b32_e64 v229, v160, v187, s[8:9]
	v_mov_b32_e32 v160, v197
	v_mov_b32_e32 v187, v197
	s_nop 1
	v_permlane32_swap_b32_e32 v160, v187
	v_cndmask_b32_e64 v231, v160, v187, s[8:9]
	v_mov_b32_e32 v160, v190
	v_mov_b32_e32 v187, v190
	s_nop 1
	v_permlane32_swap_b32_e32 v160, v187
	v_cndmask_b32_e64 v198, v160, v187, s[8:9]
	v_mov_b32_e32 v160, v194
	v_mov_b32_e32 v187, v194
	s_nop 1
	v_permlane32_swap_b32_e32 v160, v187
	v_cndmask_b32_e64 v188, v160, v187, s[8:9]
	v_mov_b32_e32 v160, v191
	v_mov_b32_e32 v187, v191
	s_nop 1
	v_permlane32_swap_b32_e32 v160, v187
	v_cndmask_b32_e64 v199, v160, v187, s[8:9]
	v_mov_b32_e32 v160, v195
	v_mov_b32_e32 v187, v195
	s_nop 1
	v_permlane32_swap_b32_e32 v160, v187
	v_cndmask_b32_e64 v189, v160, v187, s[8:9]
	s_waitcnt vmcnt(2)
	v_pk_mul_f32 v[148:149], v[148:149], v[230:231]
	s_waitcnt vmcnt(1)
	v_pk_mul_f32 v[156:157], v[156:157], v[228:229]
	s_and_saveexec_b64 s[6:7], s[10:11]
	s_xor_b64 s[6:7], exec, s[6:7]
	v_pk_mul_f32 v[158:159], v[158:159], v[198:199]
	v_pk_mul_f32 v[150:151], v[150:151], v[188:189]
	v_pk_fma_f32 v[190:191], v[190:191], v[154:155], v[158:159]
	v_pk_fma_f32 v[192:193], v[192:193], v[152:153], v[156:157]
	v_pk_fma_f32 v[194:195], v[194:195], v[146:147], v[150:151]
	v_pk_fma_f32 v[196:197], v[196:197], v[144:145], v[148:149]
	s_andn2_saveexec_b64 s[6:7], s[6:7]
	v_pk_mul_f32 v[158:159], v[158:159], v[198:199]
	v_pk_mul_f32 v[150:151], v[150:151], v[188:189]
	v_pk_fma_f32 v[190:191], v[190:191], v[154:155], v[158:159] neg_lo:[0,0,1] neg_hi:[0,0,1]
	v_pk_fma_f32 v[192:193], v[192:193], v[152:153], v[156:157] neg_lo:[0,0,1] neg_hi:[0,0,1]
	v_pk_fma_f32 v[194:195], v[194:195], v[146:147], v[150:151] neg_lo:[0,0,1] neg_hi:[0,0,1]
	v_pk_fma_f32 v[196:197], v[196:197], v[144:145], v[148:149] neg_lo:[0,0,1] neg_hi:[0,0,1]
	s_or_b64 exec, exec, s[6:7]
; __device__ __forceinline__ unsigned pk2(float lo, float hi) { return pg8::cvt_pk_bf16(lo, hi); }
;     __device__ __forceinline__ void operator()(const f32x4 (&acc)[2][2][4][2], const pg8::Unit& u, int wr, int wc, int fr, int fq) const {
;     ...
;                 for (int m = 0; m < 4; ++m) {
;                     const int rl = ai * 128 + wr * 64 + m * 16 + fr;
;                     const int row = pm * 256 + rl;
;                     float ss = 0.f;
; #pragma unroll
;                     for (int bj = 0; bj < 2; ++bj)
; #pragma unroll
;                         for (int n = 0; n < 2; ++n) { const f32x4 v = acc[ai][bj][m][n]; ss += (v[0] * v[0] + v[1] * v[1]) + (v[2] * v[2] + v[3] * v[3]); }
;                     ss = sum_fq(ss);
;                     const float rstd = __builtin_amdgcn_rsqf(ss * (1.0f / 64.0f) + EPS);
;                     const int sp = seq0 + rl;
; #pragma unroll
;                     for (int bj = 0; bj < 2; ++bj) {
;                         f32x4 y0 = acc[ai][bj][m][0] * (rstd * qscale) * gv[bj][0], y1 = acc[ai][bj][m][1] * (rstd * qscale) * gv[bj][1];
;                         if (!isctx) {
;                             const int pos = bj == 0 ? (sp >> 6) : (sp & 63);
;                             const f32x4 c0 = *(const f32x4*)(ropec + pos * 16 + fbase), c1 = *(const f32x4*)(ropec + pos * 16 + fbase + 4);
;                             const f32x4 s0 = *(const f32x4*)(ropes + pos * 16 + fbase), s1 = *(const f32x4*)(ropes + pos * 16 + fbase + 4);
;                             f32x4 p0, p1;
; #pragma unroll
;                             for (int j = 0; j < 4; ++j) { p0[j] = xor32(y0[j], lowhalf); p1[j] = xor32(y1[j], lowhalf); }
;                             if (lowhalf) { y0 = y0 * c0 - p0 * s0; y1 = y1 * c1 - p1 * s1; }
;                             else         { y0 = p0 * s0 + y0 * c0; y1 = p1 * s1 + y1 * c1; }
;                         }
;                         u32x4 w; w.x = pk2(y0[0], y0[1]); w.y = pk2(y0[2], y0[3]); w.z = pk2(y1[0], y1[1]); w.w = pk2(y1[2], y1[3]);
;                         *(u32x4*)(dst + (size_t)row * pitch + hcol + 32 * bj + 8 * fq) = w;
.LBB0_255:
	v_add_u32_e32 v144, s26, v220
	v_ashrrev_i32_e32 v145, 31, v144
	v_lshlrev_b64 v[144:145], s27, v[144:145]
	v_lshl_add_u64 v[188:189], v[144:145], 1, v[184:185]
	v_cvt_pk_bf16_f32 v248, v192, v193
	v_cvt_pk_bf16_f32 v249, v190, v191
	v_cvt_pk_bf16_f32 v250, v196, v197
	v_cvt_pk_bf16_f32 v251, v194, v195
	v_mov_b64_e32 v[252:253], v[188:189]
	v_mov_b32_e32 v187, v186
	v_pk_mul_f32 v[148:149], v[84:85], v[186:187]
	v_mov_b32_e32 v144, v186
	v_mov_b32_e32 v145, v186
	v_pk_mul_f32 v[146:147], v[86:87], v[144:145]
	v_pk_mul_f32 v[144:145], v[78:79], v[144:145]
	v_pk_mul_f32 v[190:191], v[134:135], v[146:147]
	v_pk_mul_f32 v[146:147], v[76:77], v[186:187]
	v_pk_mul_f32 v[192:193], v[132:133], v[148:149]
	v_pk_mul_f32 v[186:187], v[130:131], v[144:145]
	s_and_b64 vcc, exec, s[16:17]
	v_pk_mul_f32 v[194:195], v[128:129], v[146:147]
	s_cbranch_vccnz .Lqk_st_4
	global_load_dwordx4 v[144:147], v[176:177], off offset:2064
	global_load_dwordx4 v[152:155], v[176:177], off offset:2048
	global_load_dwordx4 v[148:151], v[178:179], off offset:2064
	global_load_dwordx4 v[156:159], v[178:179], off offset:2048
	global_store_dwordx4 v[252:253], v[248:251], off
	v_mov_b32_e32 v160, v192
	v_mov_b32_e32 v196, v192
	s_nop 1
	v_permlane32_swap_b32_e32 v160, v196
	v_cndmask_b32_e64 v228, v160, v196, s[8:9]
	v_mov_b32_e32 v160, v194
	v_mov_b32_e32 v196, v194
	s_nop 1
	v_permlane32_swap_b32_e32 v160, v196
	v_cndmask_b32_e64 v230, v160, v196, s[8:9]
	v_mov_b32_e32 v160, v193
	v_mov_b32_e32 v196, v193
	s_nop 1
	v_permlane32_swap_b32_e32 v160, v196
	v_cndmask_b32_e64 v229, v160, v196, s[8:9]
	v_mov_b32_e32 v160, v195
	v_mov_b32_e32 v196, v195
	s_nop 1
	v_permlane32_swap_b32_e32 v160, v196
	v_cndmask_b32_e64 v231, v160, v196, s[8:9]
	v_mov_b32_e32 v160, v190
	v_mov_b32_e32 v196, v190
	s_nop 1
	v_permlane32_swap_b32_e32 v160, v196
	v_cndmask_b32_e64 v198, v160, v196, s[8:9]
	v_mov_b32_e32 v160, v186
	v_mov_b32_e32 v196, v186
	s_nop 1
	v_permlane32_swap_b32_e32 v160, v196
	v_cndmask_b32_e64 v196, v160, v196, s[8:9]
	v_mov_b32_e32 v160, v191
	v_mov_b32_e32 v197, v191
	s_nop 1
	v_permlane32_swap_b32_e32 v160, v197
	v_cndmask_b32_e64 v199, v160, v197, s[8:9]
	v_mov_b32_e32 v160, v187
	v_mov_b32_e32 v197, v187
	s_nop 1
	v_permlane32_swap_b32_e32 v160, v197
	v_cndmask_b32_e64 v197, v160, v197, s[8:9]
	s_waitcnt vmcnt(2)
	v_pk_mul_f32 v[148:149], v[148:149], v[230:231]
	s_waitcnt vmcnt(1)
	v_pk_mul_f32 v[156:157], v[156:157], v[228:229]
	s_and_saveexec_b64 s[6:7], s[10:11]
	s_xor_b64 s[6:7], exec, s[6:7]
	v_pk_mul_f32 v[158:159], v[158:159], v[198:199]
	v_pk_mul_f32 v[150:151], v[150:151], v[196:197]
	v_pk_fma_f32 v[190:191], v[190:191], v[154:155], v[158:159]
	v_pk_fma_f32 v[192:193], v[192:193], v[152:153], v[156:157]
	v_pk_fma_f32 v[186:187], v[186:187], v[146:147], v[150:151]
	v_pk_fma_f32 v[194:195], v[194:195], v[144:145], v[148:149]
	s_andn2_saveexec_b64 s[6:7], s[6:7]
	v_pk_mul_f32 v[158:159], v[158:159], v[198:199]
	v_pk_mul_f32 v[150:151], v[150:151], v[196:197]
	v_pk_fma_f32 v[190:191], v[190:191], v[154:155], v[158:159] neg_lo:[0,0,1] neg_hi:[0,0,1]
	v_pk_fma_f32 v[192:193], v[192:193], v[152:153], v[156:157] neg_lo:[0,0,1] neg_hi:[0,0,1]
	v_pk_fma_f32 v[186:187], v[186:187], v[146:147], v[150:151] neg_lo:[0,0,1] neg_hi:[0,0,1]
	v_pk_fma_f32 v[194:195], v[194:195], v[144:145], v[148:149] neg_lo:[0,0,1] neg_hi:[0,0,1]
	s_or_b64 exec, exec, s[6:7]
.LBB0_261:
	v_cvt_pk_bf16_f32 v248, v192, v193
	v_cvt_pk_bf16_f32 v249, v190, v191
	v_cvt_pk_bf16_f32 v250, v194, v195
	v_cvt_pk_bf16_f32 v251, v186, v187
	v_mov_b64_e32 v[252:253], v[188:189]
	s_and_b64 vcc, exec, s[16:17]
	s_nop 0
	v_mul_f32_e32 v144, v81, v81
	v_mul_f32_e32 v145, v83, v83
	v_fmac_f32_e32 v144, v80, v80
	v_fmac_f32_e32 v145, v82, v82
	v_add_f32_e32 v144, v144, v145
	v_mul_f32_e32 v145, v73, v73
	v_mul_f32_e32 v146, v75, v75
	v_fmac_f32_e32 v145, v72, v72
	v_fmac_f32_e32 v146, v74, v74
	v_add_f32_e32 v145, v145, v146
	v_add_f32_e32 v144, v144, v145
	v_mul_f32_e32 v145, v69, v69
	v_mul_f32_e32 v146, v71, v71
	v_fmac_f32_e32 v145, v68, v68
	v_fmac_f32_e32 v146, v70, v70
	v_add_f32_e32 v145, v145, v146
	v_add_f32_e32 v144, v144, v145
	v_mul_f32_e32 v145, v65, v65
	v_mul_f32_e32 v146, v67, v67
	v_fmac_f32_e32 v145, v64, v64
	v_fmac_f32_e32 v146, v66, v66
	v_add_f32_e32 v145, v145, v146
	v_add_f32_e32 v144, v144, v145
	v_mov_b32_e32 v145, v144
	s_nop 1
	v_permlane16_swap_b32_e32 v144, v145
	v_add_f32_e32 v144, v144, v145
	v_mov_b32_e32 v145, v144
	s_nop 1
	v_permlane32_swap_b32_e32 v144, v145
	v_add_f32_e32 v144, v144, v145
	v_fmamk_f32 v144, v144, 0x3c800000, v200
	v_rsq_f32_e32 v144, v144
	s_nop 0
	v_mul_f32_e32 v186, v227, v144
	v_pk_mul_f32 v[144:145], v[80:81], v[186:187] op_sel_hi:[1,0]
	v_pk_mul_f32 v[146:147], v[82:83], v[186:187] op_sel_hi:[1,0]
	v_pk_mul_f32 v[192:193], v[140:141], v[144:145]
	v_pk_mul_f32 v[190:191], v[142:143], v[146:147]
	v_pk_mul_f32 v[144:145], v[72:73], v[186:187] op_sel_hi:[1,0]
	v_pk_mul_f32 v[146:147], v[74:75], v[186:187] op_sel_hi:[1,0]
	v_pk_mul_f32 v[196:197], v[136:137], v[144:145]
	v_pk_mul_f32 v[194:195], v[138:139], v[146:147]
	s_cbranch_vccnz .Lqk_st_5
; __device__ __forceinline__ unsigned pk2(float lo, float hi) { return pg8::cvt_pk_bf16(lo, hi); }
;     __device__ __forceinline__ void operator()(const f32x4 (&acc)[2][2][4][2], const pg8::Unit& u, int wr, int wc, int fr, int fq) const {
;     ...
;                     const int sp = seq0 + rl;
; #pragma unroll
;                     for (int bj = 0; bj < 2; ++bj) {
;                         f32x4 y0 = acc[ai][bj][m][0] * (rstd * qscale) * gv[bj][0], y1 = acc[ai][bj][m][1] * (rstd * qscale) * gv[bj][1];
;                         if (!isctx) {
;                             const int pos = bj == 0 ? (sp >> 6) : (sp & 63);
;                             const f32x4 c0 = *(const f32x4*)(ropec + pos * 16 + fbase), c1 = *(const f32x4*)(ropec + pos * 16 + fbase + 4);
;                             const f32x4 s0 = *(const f32x4*)(ropes + pos * 16 + fbase), s1 = *(const f32x4*)(ropes + pos * 16 + fbase + 4);
;                             f32x4 p0, p1;
; #pragma unroll
;                             for (int j = 0; j < 4; ++j) { p0[j] = xor32(y0[j], lowhalf); p1[j] = xor32(y1[j], lowhalf); }
;                             if (lowhalf) { y0 = y0 * c0 - p0 * s0; y1 = y1 * c1 - p1 * s1; }
;                             else         { y0 = p0 * s0 + y0 * c0; y1 = p1 * s1 + y1 * c1; }
;                         }
;                         u32x4 w; w.x = pk2(y0[0], y0[1]); w.y = pk2(y0[2], y0[3]); w.z = pk2(y1[0], y1[1]); w.w = pk2(y1[2], y1[3]);
;                         *(u32x4*)(dst + (size_t)row * pitch + hcol + 32 * bj + 8 * fq) = w;
	v_add_u32_e32 v144, s5, v221
	v_ashrrev_i32_e32 v144, 2, v144
	v_and_b32_e32 v144, -16, v144
	v_ashrrev_i32_e32 v145, 31, v144
	v_lshlrev_b64 v[148:149], 2, v[144:145]
	v_lshl_add_u64 v[150:151], v[172:173], 0, v[148:149]
	v_lshl_add_u64 v[156:157], v[174:175], 0, v[148:149]
	global_load_dwordx4 v[144:147], v[150:151], off offset:16
	global_load_dwordx4 v[152:155], v[150:151], off
	s_nop 0
	global_load_dwordx4 v[148:151], v[156:157], off offset:16
	s_nop 0
	global_load_dwordx4 v[156:159], v[156:157], off
	global_store_dwordx4 v[252:253], v[248:251], off offset:64
	v_mov_b32_e32 v160, v192
	v_mov_b32_e32 v187, v192
	s_nop 1
	v_permlane32_swap_b32_e32 v160, v187
	v_cndmask_b32_e64 v228, v160, v187, s[8:9]
	v_mov_b32_e32 v160, v196
	v_mov_b32_e32 v187, v196
	s_nop 1
	v_permlane32_swap_b32_e32 v160, v187
	v_cndmask_b32_e64 v230, v160, v187, s[8:9]
	v_mov_b32_e32 v160, v193
	v_mov_b32_e32 v187, v193
	s_nop 1
	v_permlane32_swap_b32_e32 v160, v187
	v_cndmask_b32_e64 v229, v160, v187, s[8:9]
	v_mov_b32_e32 v160, v197
	v_mov_b32_e32 v187, v197
	s_nop 1
	v_permlane32_swap_b32_e32 v160, v187
	v_cndmask_b32_e64 v231, v160, v187, s[8:9]
	v_mov_b32_e32 v160, v190
	v_mov_b32_e32 v187, v190
	s_nop 1
	v_permlane32_swap_b32_e32 v160, v187
	v_cndmask_b32_e64 v198, v160, v187, s[8:9]
	v_mov_b32_e32 v160, v194
	v_mov_b32_e32 v187, v194
	s_nop 1
	v_permlane32_swap_b32_e32 v160, v187
	v_cndmask_b32_e64 v188, v160, v187, s[8:9]
	v_mov_b32_e32 v160, v191
	v_mov_b32_e32 v187, v191
	s_nop 1
	v_permlane32_swap_b32_e32 v160, v187
	v_cndmask_b32_e64 v199, v160, v187, s[8:9]
	v_mov_b32_e32 v160, v195
	v_mov_b32_e32 v187, v195
	s_nop 1
	v_permlane32_swap_b32_e32 v160, v187
	v_cndmask_b32_e64 v189, v160, v187, s[8:9]
	s_waitcnt vmcnt(2)
	v_pk_mul_f32 v[148:149], v[148:149], v[230:231]
	s_waitcnt vmcnt(1)
	v_pk_mul_f32 v[156:157], v[156:157], v[228:229]
	s_and_saveexec_b64 s[6:7], s[10:11]
	s_xor_b64 s[6:7], exec, s[6:7]
	v_pk_mul_f32 v[158:159], v[158:159], v[198:199]
	v_pk_mul_f32 v[150:151], v[150:151], v[188:189]
	v_pk_fma_f32 v[190:191], v[190:191], v[154:155], v[158:159]
	v_pk_fma_f32 v[192:193], v[192:193], v[152:153], v[156:157]
	v_pk_fma_f32 v[194:195], v[194:195], v[146:147], v[150:151]
	v_pk_fma_f32 v[196:197], v[196:197], v[144:145], v[148:149]
	s_andn2_saveexec_b64 s[6:7], s[6:7]
	v_pk_mul_f32 v[158:159], v[158:159], v[198:199]
	v_pk_mul_f32 v[150:151], v[150:151], v[188:189]
	v_pk_fma_f32 v[190:191], v[190:191], v[154:155], v[158:159] neg_lo:[0,0,1] neg_hi:[0,0,1]
	v_pk_fma_f32 v[192:193], v[192:193], v[152:153], v[156:157] neg_lo:[0,0,1] neg_hi:[0,0,1]
	v_pk_fma_f32 v[194:195], v[194:195], v[146:147], v[150:151] neg_lo:[0,0,1] neg_hi:[0,0,1]
	v_pk_fma_f32 v[196:197], v[196:197], v[144:145], v[148:149] neg_lo:[0,0,1] neg_hi:[0,0,1]
	s_or_b64 exec, exec, s[6:7]
.LBB0_267:
	v_add_u32_e32 v144, s26, v221
	v_ashrrev_i32_e32 v145, 31, v144
	v_lshlrev_b64 v[144:145], s27, v[144:145]
	v_lshl_add_u64 v[188:189], v[144:145], 1, v[184:185]
	v_cvt_pk_bf16_f32 v248, v192, v193
	v_cvt_pk_bf16_f32 v249, v190, v191
	v_cvt_pk_bf16_f32 v250, v196, v197
	v_cvt_pk_bf16_f32 v251, v194, v195
	v_mov_b64_e32 v[252:253], v[188:189]
	v_mov_b32_e32 v187, v186
	v_pk_mul_f32 v[148:149], v[68:69], v[186:187]
	v_mov_b32_e32 v144, v186
	v_mov_b32_e32 v145, v186
	v_pk_mul_f32 v[146:147], v[70:71], v[144:145]
	v_pk_mul_f32 v[144:145], v[66:67], v[144:145]
	v_pk_mul_f32 v[190:191], v[134:135], v[146:147]
	v_pk_mul_f32 v[146:147], v[64:65], v[186:187]
	v_pk_mul_f32 v[192:193], v[132:133], v[148:149]
	v_pk_mul_f32 v[186:187], v[130:131], v[144:145]
	s_and_b64 vcc, exec, s[16:17]
	v_pk_mul_f32 v[194:195], v[128:129], v[146:147]
	s_cbranch_vccnz .Lqk_st_6
	global_load_dwordx4 v[144:147], v[176:177], off offset:3088
	global_load_dwordx4 v[152:155], v[176:177], off offset:3072
	global_load_dwordx4 v[148:151], v[178:179], off offset:3088
	global_load_dwordx4 v[156:159], v[178:179], off offset:3072
	global_store_dwordx4 v[252:253], v[248:251], off
	v_mov_b32_e32 v160, v192
	v_mov_b32_e32 v196, v192
	s_nop 1
	v_permlane32_swap_b32_e32 v160, v196
	v_cndmask_b32_e64 v228, v160, v196, s[8:9]
	v_mov_b32_e32 v160, v194
	v_mov_b32_e32 v196, v194
	s_nop 1
	v_permlane32_swap_b32_e32 v160, v196
	v_cndmask_b32_e64 v230, v160, v196, s[8:9]
	v_mov_b32_e32 v160, v193
	v_mov_b32_e32 v196, v193
	s_nop 1
	v_permlane32_swap_b32_e32 v160, v196
	v_cndmask_b32_e64 v229, v160, v196, s[8:9]
	v_mov_b32_e32 v160, v195
	v_mov_b32_e32 v196, v195
	s_nop 1
	v_permlane32_swap_b32_e32 v160, v196
	v_cndmask_b32_e64 v231, v160, v196, s[8:9]
	v_mov_b32_e32 v160, v190
	v_mov_b32_e32 v196, v190
	s_nop 1
	v_permlane32_swap_b32_e32 v160, v196
	v_cndmask_b32_e64 v198, v160, v196, s[8:9]
	v_mov_b32_e32 v160, v186
	v_mov_b32_e32 v196, v186
	s_nop 1
	v_permlane32_swap_b32_e32 v160, v196
	v_cndmask_b32_e64 v196, v160, v196, s[8:9]
	v_mov_b32_e32 v160, v191
	v_mov_b32_e32 v197, v191
	s_nop 1
	v_permlane32_swap_b32_e32 v160, v197
	v_cndmask_b32_e64 v199, v160, v197, s[8:9]
	v_mov_b32_e32 v160, v187
	v_mov_b32_e32 v197, v187
	s_nop 1
	v_permlane32_swap_b32_e32 v160, v197
	v_cndmask_b32_e64 v197, v160, v197, s[8:9]
	s_waitcnt vmcnt(2)
	v_pk_mul_f32 v[148:149], v[148:149], v[230:231]
	s_waitcnt vmcnt(1)
	v_pk_mul_f32 v[156:157], v[156:157], v[228:229]
	s_and_saveexec_b64 s[6:7], s[10:11]
	s_xor_b64 s[6:7], exec, s[6:7]
	v_pk_mul_f32 v[158:159], v[158:159], v[198:199]
	v_pk_mul_f32 v[150:151], v[150:151], v[196:197]
	v_pk_fma_f32 v[190:191], v[190:191], v[154:155], v[158:159]
	v_pk_fma_f32 v[192:193], v[192:193], v[152:153], v[156:157]
	v_pk_fma_f32 v[186:187], v[186:187], v[146:147], v[150:151]
	v_pk_fma_f32 v[194:195], v[194:195], v[144:145], v[148:149]
	s_andn2_saveexec_b64 s[6:7], s[6:7]
	v_pk_mul_f32 v[158:159], v[158:159], v[198:199]
	v_pk_mul_f32 v[150:151], v[150:151], v[196:197]
	v_pk_fma_f32 v[190:191], v[190:191], v[154:155], v[158:159] neg_lo:[0,0,1] neg_hi:[0,0,1]
	v_pk_fma_f32 v[192:193], v[192:193], v[152:153], v[156:157] neg_lo:[0,0,1] neg_hi:[0,0,1]
	v_pk_fma_f32 v[186:187], v[186:187], v[146:147], v[150:151] neg_lo:[0,0,1] neg_hi:[0,0,1]
	v_pk_fma_f32 v[194:195], v[194:195], v[144:145], v[148:149] neg_lo:[0,0,1] neg_hi:[0,0,1]
	s_or_b64 exec, exec, s[6:7]
; __device__ __forceinline__ unsigned pk2(float lo, float hi) { return pg8::cvt_pk_bf16(lo, hi); }
;     __device__ __forceinline__ void operator()(const f32x4 (&acc)[2][2][4][2], const pg8::Unit& u, int wr, int wc, int fr, int fq) const {
;     ...
;                 for (int m = 0; m < 4; ++m) {
;                     const int rl = ai * 128 + wr * 64 + m * 16 + fr;
;                     const int row = pm * 256 + rl;
;                     float ss = 0.f;
; #pragma unroll
;                     for (int bj = 0; bj < 2; ++bj)
; #pragma unroll
;                         for (int n = 0; n < 2; ++n) { const f32x4 v = acc[ai][bj][m][n]; ss += (v[0] * v[0] + v[1] * v[1]) + (v[2] * v[2] + v[3] * v[3]); }
;                     ss = sum_fq(ss);
;                     const float rstd = __builtin_amdgcn_rsqf(ss * (1.0f / 64.0f) + EPS);
;                     const int sp = seq0 + rl;
; #pragma unroll
;                     for (int bj = 0; bj < 2; ++bj) {
;                         f32x4 y0 = acc[ai][bj][m][0] * (rstd * qscale) * gv[bj][0], y1 = acc[ai][bj][m][1] * (rstd * qscale) * gv[bj][1];
;                         if (!isctx) {
;                             const int pos = bj == 0 ? (sp >> 6) : (sp & 63);
;                             const f32x4 c0 = *(const f32x4*)(ropec + pos * 16 + fbase), c1 = *(const f32x4*)(ropec + pos * 16 + fbase + 4);
;                             const f32x4 s0 = *(const f32x4*)(ropes + pos * 16 + fbase), s1 = *(const f32x4*)(ropes + pos * 16 + fbase + 4);
;                             f32x4 p0, p1;
; #pragma unroll
;                             for (int j = 0; j < 4; ++j) { p0[j] = xor32(y0[j], lowhalf); p1[j] = xor32(y1[j], lowhalf); }
;                             if (lowhalf) { y0 = y0 * c0 - p0 * s0; y1 = y1 * c1 - p1 * s1; }
;                             else         { y0 = p0 * s0 + y0 * c0; y1 = p1 * s1 + y1 * c1; }
;                         }
;                         u32x4 w; w.x = pk2(y0[0], y0[1]); w.y = pk2(y0[2], y0[3]); w.z = pk2(y1[0], y1[1]); w.w = pk2(y1[2], y1[3]);
;                         *(u32x4*)(dst + (size_t)row * pitch + hcol + 32 * bj + 8 * fq) = w;
.LBB0_273:
	v_cvt_pk_bf16_f32 v248, v192, v193
	v_cvt_pk_bf16_f32 v249, v190, v191
	v_cvt_pk_bf16_f32 v250, v194, v195
	v_cvt_pk_bf16_f32 v251, v186, v187
	v_mov_b64_e32 v[252:253], v[188:189]
	s_and_b64 vcc, exec, s[16:17]
	s_nop 0
	v_mul_f32_e32 v144, v61, v61
	v_mul_f32_e32 v145, v63, v63
	v_fmac_f32_e32 v144, v60, v60
	v_fmac_f32_e32 v145, v62, v62
	v_add_f32_e32 v144, v144, v145
	v_mul_f32_e32 v145, v57, v57
	v_mul_f32_e32 v146, v59, v59
	v_fmac_f32_e32 v145, v56, v56
	v_fmac_f32_e32 v146, v58, v58
	v_add_f32_e32 v145, v145, v146
	v_add_f32_e32 v144, v144, v145
	v_mul_f32_e32 v145, v53, v53
	v_mul_f32_e32 v146, v55, v55
	v_fmac_f32_e32 v145, v52, v52
	v_fmac_f32_e32 v146, v54, v54
	v_add_f32_e32 v145, v145, v146
	v_add_f32_e32 v144, v144, v145
	v_mul_f32_e32 v145, v45, v45
	v_mul_f32_e32 v146, v47, v47
	v_fmac_f32_e32 v145, v44, v44
	v_fmac_f32_e32 v146, v46, v46
	v_add_f32_e32 v145, v145, v146
	v_add_f32_e32 v144, v144, v145
	v_mov_b32_e32 v145, v144
	s_nop 1
	v_permlane16_swap_b32_e32 v144, v145
	v_add_f32_e32 v144, v144, v145
	v_mov_b32_e32 v145, v144
	s_nop 1
	v_permlane32_swap_b32_e32 v144, v145
	v_add_f32_e32 v144, v144, v145
	v_fmamk_f32 v144, v144, 0x3c800000, v200
	v_rsq_f32_e32 v144, v144
	s_nop 0
	v_mul_f32_e32 v186, v227, v144
	v_pk_mul_f32 v[144:145], v[60:61], v[186:187] op_sel_hi:[1,0]
	v_pk_mul_f32 v[146:147], v[62:63], v[186:187] op_sel_hi:[1,0]
	v_pk_mul_f32 v[192:193], v[140:141], v[144:145]
	v_pk_mul_f32 v[190:191], v[142:143], v[146:147]
	v_pk_mul_f32 v[144:145], v[56:57], v[186:187] op_sel_hi:[1,0]
	v_pk_mul_f32 v[146:147], v[58:59], v[186:187] op_sel_hi:[1,0]
	v_pk_mul_f32 v[196:197], v[136:137], v[144:145]
	v_pk_mul_f32 v[194:195], v[138:139], v[146:147]
	s_cbranch_vccnz .Lqk_st_7
	v_add_u32_e32 v144, s5, v222
	v_ashrrev_i32_e32 v144, 2, v144
	v_and_b32_e32 v144, -16, v144
	v_ashrrev_i32_e32 v145, 31, v144
	v_lshlrev_b64 v[148:149], 2, v[144:145]
	v_lshl_add_u64 v[150:151], v[172:173], 0, v[148:149]
	v_lshl_add_u64 v[156:157], v[174:175], 0, v[148:149]
	global_load_dwordx4 v[144:147], v[150:151], off offset:16
	global_load_dwordx4 v[152:155], v[150:151], off
	s_nop 0
	global_load_dwordx4 v[148:151], v[156:157], off offset:16
	s_nop 0
	global_load_dwordx4 v[156:159], v[156:157], off
	global_store_dwordx4 v[252:253], v[248:251], off offset:64
	v_mov_b32_e32 v160, v192
	v_mov_b32_e32 v187, v192
	s_nop 1
	v_permlane32_swap_b32_e32 v160, v187
	v_cndmask_b32_e64 v228, v160, v187, s[8:9]
	v_mov_b32_e32 v160, v196
	v_mov_b32_e32 v187, v196
	s_nop 1
	v_permlane32_swap_b32_e32 v160, v187
	v_cndmask_b32_e64 v230, v160, v187, s[8:9]
	v_mov_b32_e32 v160, v193
	v_mov_b32_e32 v187, v193
	s_nop 1
	v_permlane32_swap_b32_e32 v160, v187
	v_cndmask_b32_e64 v229, v160, v187, s[8:9]
	v_mov_b32_e32 v160, v197
	v_mov_b32_e32 v187, v197
	s_nop 1
	v_permlane32_swap_b32_e32 v160, v187
	v_cndmask_b32_e64 v231, v160, v187, s[8:9]
	v_mov_b32_e32 v160, v190
	v_mov_b32_e32 v187, v190
	s_nop 1
	v_permlane32_swap_b32_e32 v160, v187
	v_cndmask_b32_e64 v198, v160, v187, s[8:9]
	v_mov_b32_e32 v160, v194
	v_mov_b32_e32 v187, v194
	s_nop 1
	v_permlane32_swap_b32_e32 v160, v187
	v_cndmask_b32_e64 v188, v160, v187, s[8:9]
	v_mov_b32_e32 v160, v191
	v_mov_b32_e32 v187, v191
	s_nop 1
	v_permlane32_swap_b32_e32 v160, v187
	v_cndmask_b32_e64 v199, v160, v187, s[8:9]
	v_mov_b32_e32 v160, v195
	v_mov_b32_e32 v187, v195
	s_nop 1
	v_permlane32_swap_b32_e32 v160, v187
	v_cndmask_b32_e64 v189, v160, v187, s[8:9]
	s_waitcnt vmcnt(2)
	v_pk_mul_f32 v[148:149], v[148:149], v[230:231]
	s_waitcnt vmcnt(1)
	v_pk_mul_f32 v[156:157], v[156:157], v[228:229]
	s_and_saveexec_b64 s[6:7], s[10:11]
	s_xor_b64 s[6:7], exec, s[6:7]
	v_pk_mul_f32 v[158:159], v[158:159], v[198:199]
	v_pk_mul_f32 v[150:151], v[150:151], v[188:189]
	v_pk_fma_f32 v[190:191], v[190:191], v[154:155], v[158:159]
	v_pk_fma_f32 v[192:193], v[192:193], v[152:153], v[156:157]
	v_pk_fma_f32 v[194:195], v[194:195], v[146:147], v[150:151]
	v_pk_fma_f32 v[196:197], v[196:197], v[144:145], v[148:149]
	s_andn2_saveexec_b64 s[6:7], s[6:7]
	v_pk_mul_f32 v[158:159], v[158:159], v[198:199]
	v_pk_mul_f32 v[150:151], v[150:151], v[188:189]
	v_pk_fma_f32 v[190:191], v[190:191], v[154:155], v[158:159] neg_lo:[0,0,1] neg_hi:[0,0,1]
	v_pk_fma_f32 v[192:193], v[192:193], v[152:153], v[156:157] neg_lo:[0,0,1] neg_hi:[0,0,1]
	v_pk_fma_f32 v[194:195], v[194:195], v[146:147], v[150:151] neg_lo:[0,0,1] neg_hi:[0,0,1]
	v_pk_fma_f32 v[196:197], v[196:197], v[144:145], v[148:149] neg_lo:[0,0,1] neg_hi:[0,0,1]
	s_or_b64 exec, exec, s[6:7]
; __device__ __forceinline__ unsigned pk2(float lo, float hi) { return pg8::cvt_pk_bf16(lo, hi); }
;     __device__ __forceinline__ void operator()(const f32x4 (&acc)[2][2][4][2], const pg8::Unit& u, int wr, int wc, int fr, int fq) const {
;     ...
;                 for (int m = 0; m < 4; ++m) {
;                     const int rl = ai * 128 + wr * 64 + m * 16 + fr;
;                     const int row = pm * 256 + rl;
;                     float ss = 0.f;
; #pragma unroll
;                     for (int bj = 0; bj < 2; ++bj)
; #pragma unroll
;                         for (int n = 0; n < 2; ++n) { const f32x4 v = acc[ai][bj][m][n]; ss += (v[0] * v[0] + v[1] * v[1]) + (v[2] * v[2] + v[3] * v[3]); }
;                     ss = sum_fq(ss);
;                     const float rstd = __builtin_amdgcn_rsqf(ss * (1.0f / 64.0f) + EPS);
;                     const int sp = seq0 + rl;
; #pragma unroll
;                     for (int bj = 0; bj < 2; ++bj) {
;                         f32x4 y0 = acc[ai][bj][m][0] * (rstd * qscale) * gv[bj][0], y1 = acc[ai][bj][m][1] * (rstd * qscale) * gv[bj][1];
;                         if (!isctx) {
;                             const int pos = bj == 0 ? (sp >> 6) : (sp & 63);
;                             const f32x4 c0 = *(const f32x4*)(ropec + pos * 16 + fbase), c1 = *(const f32x4*)(ropec + pos * 16 + fbase + 4);
;                             const f32x4 s0 = *(const f32x4*)(ropes + pos * 16 + fbase), s1 = *(const f32x4*)(ropes + pos * 16 + fbase + 4);
;                             f32x4 p0, p1;
; #pragma unroll
;                             for (int j = 0; j < 4; ++j) { p0[j] = xor32(y0[j], lowhalf); p1[j] = xor32(y1[j], lowhalf); }
;                             if (lowhalf) { y0 = y0 * c0 - p0 * s0; y1 = y1 * c1 - p1 * s1; }
;                             else         { y0 = p0 * s0 + y0 * c0; y1 = p1 * s1 + y1 * c1; }
;                         }
;                         u32x4 w; w.x = pk2(y0[0], y0[1]); w.y = pk2(y0[2], y0[3]); w.z = pk2(y1[0], y1[1]); w.w = pk2(y1[2], y1[3]);
;                         *(u32x4*)(dst + (size_t)row * pitch + hcol + 32 * bj + 8 * fq) = w;
.LBB0_279:
	v_add_u32_e32 v144, s26, v222
	v_ashrrev_i32_e32 v145, 31, v144
	v_lshlrev_b64 v[144:145], s27, v[144:145]
	v_lshl_add_u64 v[188:189], v[144:145], 1, v[184:185]
	v_cvt_pk_bf16_f32 v248, v192, v193
	v_cvt_pk_bf16_f32 v249, v190, v191
	v_cvt_pk_bf16_f32 v250, v196, v197
	v_cvt_pk_bf16_f32 v251, v194, v195
	v_mov_b64_e32 v[252:253], v[188:189]
	v_mov_b32_e32 v187, v186
	v_pk_mul_f32 v[148:149], v[52:53], v[186:187]
	v_mov_b32_e32 v144, v186
	v_mov_b32_e32 v145, v186
	v_pk_mul_f32 v[146:147], v[54:55], v[144:145]
	v_pk_mul_f32 v[144:145], v[46:47], v[144:145]
	v_pk_mul_f32 v[190:191], v[134:135], v[146:147]
	v_pk_mul_f32 v[146:147], v[44:45], v[186:187]
	v_pk_mul_f32 v[192:193], v[132:133], v[148:149]
	v_pk_mul_f32 v[186:187], v[130:131], v[144:145]
	s_and_b64 vcc, exec, s[16:17]
	v_pk_mul_f32 v[194:195], v[128:129], v[146:147]
	s_cbranch_vccnz .Lqk_st_8
	global_load_dwordx4 v[144:147], v[176:177], off offset:16
	global_load_dwordx4 v[152:155], v[176:177], off
	global_load_dwordx4 v[148:151], v[178:179], off offset:16
	global_load_dwordx4 v[156:159], v[178:179], off
	global_store_dwordx4 v[252:253], v[248:251], off
	v_mov_b32_e32 v160, v192
	v_mov_b32_e32 v196, v192
	s_nop 1
	v_permlane32_swap_b32_e32 v160, v196
	v_cndmask_b32_e64 v228, v160, v196, s[8:9]
	v_mov_b32_e32 v160, v194
	v_mov_b32_e32 v196, v194
	s_nop 1
	v_permlane32_swap_b32_e32 v160, v196
	v_cndmask_b32_e64 v230, v160, v196, s[8:9]
	v_mov_b32_e32 v160, v193
	v_mov_b32_e32 v196, v193
	s_nop 1
	v_permlane32_swap_b32_e32 v160, v196
	v_cndmask_b32_e64 v229, v160, v196, s[8:9]
	v_mov_b32_e32 v160, v195
	v_mov_b32_e32 v196, v195
	s_nop 1
	v_permlane32_swap_b32_e32 v160, v196
	v_cndmask_b32_e64 v231, v160, v196, s[8:9]
	v_mov_b32_e32 v160, v190
	v_mov_b32_e32 v196, v190
	s_nop 1
	v_permlane32_swap_b32_e32 v160, v196
	v_cndmask_b32_e64 v198, v160, v196, s[8:9]
	v_mov_b32_e32 v160, v186
	v_mov_b32_e32 v196, v186
	s_nop 1
	v_permlane32_swap_b32_e32 v160, v196
	v_cndmask_b32_e64 v196, v160, v196, s[8:9]
	v_mov_b32_e32 v160, v191
	v_mov_b32_e32 v197, v191
	s_nop 1
	v_permlane32_swap_b32_e32 v160, v197
	v_cndmask_b32_e64 v199, v160, v197, s[8:9]
	v_mov_b32_e32 v160, v187
	v_mov_b32_e32 v197, v187
	s_nop 1
	v_permlane32_swap_b32_e32 v160, v197
	v_cndmask_b32_e64 v197, v160, v197, s[8:9]
	s_waitcnt vmcnt(2)
	v_pk_mul_f32 v[148:149], v[148:149], v[230:231]
	s_waitcnt vmcnt(1)
	v_pk_mul_f32 v[156:157], v[156:157], v[228:229]
	s_and_saveexec_b64 s[6:7], s[10:11]
	s_xor_b64 s[6:7], exec, s[6:7]
	v_pk_mul_f32 v[158:159], v[158:159], v[198:199]
	v_pk_mul_f32 v[150:151], v[150:151], v[196:197]
	v_pk_fma_f32 v[190:191], v[190:191], v[154:155], v[158:159]
	v_pk_fma_f32 v[192:193], v[192:193], v[152:153], v[156:157]
	v_pk_fma_f32 v[186:187], v[186:187], v[146:147], v[150:151]
	v_pk_fma_f32 v[194:195], v[194:195], v[144:145], v[148:149]
	s_andn2_saveexec_b64 s[6:7], s[6:7]
	v_pk_mul_f32 v[158:159], v[158:159], v[198:199]
	v_pk_mul_f32 v[150:151], v[150:151], v[196:197]
	v_pk_fma_f32 v[190:191], v[190:191], v[154:155], v[158:159] neg_lo:[0,0,1] neg_hi:[0,0,1]
	v_pk_fma_f32 v[192:193], v[192:193], v[152:153], v[156:157] neg_lo:[0,0,1] neg_hi:[0,0,1]
	v_pk_fma_f32 v[186:187], v[186:187], v[146:147], v[150:151] neg_lo:[0,0,1] neg_hi:[0,0,1]
	v_pk_fma_f32 v[194:195], v[194:195], v[144:145], v[148:149] neg_lo:[0,0,1] neg_hi:[0,0,1]
	s_or_b64 exec, exec, s[6:7]
.LBB0_285:
	v_cvt_pk_bf16_f32 v248, v192, v193
	v_cvt_pk_bf16_f32 v249, v190, v191
	v_cvt_pk_bf16_f32 v250, v194, v195
	v_cvt_pk_bf16_f32 v251, v186, v187
	v_mov_b64_e32 v[252:253], v[188:189]
	s_and_b64 vcc, exec, s[16:17]
	s_nop 0
	v_mul_f32_e32 v144, v49, v49
	v_mul_f32_e32 v145, v51, v51
	v_fmac_f32_e32 v144, v48, v48
	v_fmac_f32_e32 v145, v50, v50
	v_add_f32_e32 v144, v144, v145
	v_mul_f32_e32 v145, v41, v41
	v_mul_f32_e32 v146, v43, v43
	v_fmac_f32_e32 v145, v40, v40
	v_fmac_f32_e32 v146, v42, v42
	v_add_f32_e32 v145, v145, v146
	v_add_f32_e32 v144, v144, v145
	v_mul_f32_e32 v145, v37, v37
	v_mul_f32_e32 v146, v39, v39
	v_fmac_f32_e32 v145, v36, v36
	v_fmac_f32_e32 v146, v38, v38
	v_add_f32_e32 v145, v145, v146
	v_add_f32_e32 v144, v144, v145
	v_mul_f32_e32 v145, v29, v29
	v_mul_f32_e32 v146, v31, v31
	v_fmac_f32_e32 v145, v28, v28
	v_fmac_f32_e32 v146, v30, v30
	v_add_f32_e32 v145, v145, v146
	v_add_f32_e32 v144, v144, v145
	v_mov_b32_e32 v145, v144
	s_nop 1
	v_permlane16_swap_b32_e32 v144, v145
	v_add_f32_e32 v144, v144, v145
	v_mov_b32_e32 v145, v144
	s_nop 1
	v_permlane32_swap_b32_e32 v144, v145
	v_add_f32_e32 v144, v144, v145
	v_fmamk_f32 v144, v144, 0x3c800000, v200
	v_rsq_f32_e32 v144, v144
	s_nop 0
	v_mul_f32_e32 v186, v227, v144
	v_pk_mul_f32 v[144:145], v[48:49], v[186:187] op_sel_hi:[1,0]
	v_pk_mul_f32 v[146:147], v[50:51], v[186:187] op_sel_hi:[1,0]
	v_pk_mul_f32 v[192:193], v[140:141], v[144:145]
	v_pk_mul_f32 v[190:191], v[142:143], v[146:147]
	v_pk_mul_f32 v[144:145], v[40:41], v[186:187] op_sel_hi:[1,0]
	v_pk_mul_f32 v[146:147], v[42:43], v[186:187] op_sel_hi:[1,0]
	v_pk_mul_f32 v[196:197], v[136:137], v[144:145]
	v_pk_mul_f32 v[194:195], v[138:139], v[146:147]
	s_cbranch_vccnz .Lqk_st_9
; __device__ __forceinline__ unsigned pk2(float lo, float hi) { return pg8::cvt_pk_bf16(lo, hi); }
;     __device__ __forceinline__ void operator()(const f32x4 (&acc)[2][2][4][2], const pg8::Unit& u, int wr, int wc, int fr, int fq) const {
;     ...
;                     const int sp = seq0 + rl;
; #pragma unroll
;                     for (int bj = 0; bj < 2; ++bj) {
;                         f32x4 y0 = acc[ai][bj][m][0] * (rstd * qscale) * gv[bj][0], y1 = acc[ai][bj][m][1] * (rstd * qscale) * gv[bj][1];
;                         if (!isctx) {
;                             const int pos = bj == 0 ? (sp >> 6) : (sp & 63);
;                             const f32x4 c0 = *(const f32x4*)(ropec + pos * 16 + fbase), c1 = *(const f32x4*)(ropec + pos * 16 + fbase + 4);
;                             const f32x4 s0 = *(const f32x4*)(ropes + pos * 16 + fbase), s1 = *(const f32x4*)(ropes + pos * 16 + fbase + 4);
;                             f32x4 p0, p1;
; #pragma unroll
;                             for (int j = 0; j < 4; ++j) { p0[j] = xor32(y0[j], lowhalf); p1[j] = xor32(y1[j], lowhalf); }
;                             if (lowhalf) { y0 = y0 * c0 - p0 * s0; y1 = y1 * c1 - p1 * s1; }
;                             else         { y0 = p0 * s0 + y0 * c0; y1 = p1 * s1 + y1 * c1; }
;                         }
;                         u32x4 w; w.x = pk2(y0[0], y0[1]); w.y = pk2(y0[2], y0[3]); w.z = pk2(y1[0], y1[1]); w.w = pk2(y1[2], y1[3]);
;                         *(u32x4*)(dst + (size_t)row * pitch + hcol + 32 * bj + 8 * fq) = w;
	v_add_u32_e32 v144, s5, v223
	v_ashrrev_i32_e32 v144, 2, v144
	v_and_b32_e32 v144, -16, v144
	v_ashrrev_i32_e32 v145, 31, v144
	v_lshlrev_b64 v[148:149], 2, v[144:145]
	v_lshl_add_u64 v[150:151], v[172:173], 0, v[148:149]
	v_lshl_add_u64 v[156:157], v[174:175], 0, v[148:149]
	global_load_dwordx4 v[144:147], v[150:151], off offset:16
	global_load_dwordx4 v[152:155], v[150:151], off
	s_nop 0
	global_load_dwordx4 v[148:151], v[156:157], off offset:16
	s_nop 0
	global_load_dwordx4 v[156:159], v[156:157], off
	global_store_dwordx4 v[252:253], v[248:251], off offset:64
	v_mov_b32_e32 v160, v192
	v_mov_b32_e32 v187, v192
	s_nop 1
	v_permlane32_swap_b32_e32 v160, v187
	v_cndmask_b32_e64 v228, v160, v187, s[8:9]
	v_mov_b32_e32 v160, v196
	v_mov_b32_e32 v187, v196
	s_nop 1
	v_permlane32_swap_b32_e32 v160, v187
	v_cndmask_b32_e64 v230, v160, v187, s[8:9]
	v_mov_b32_e32 v160, v193
	v_mov_b32_e32 v187, v193
	s_nop 1
	v_permlane32_swap_b32_e32 v160, v187
	v_cndmask_b32_e64 v229, v160, v187, s[8:9]
	v_mov_b32_e32 v160, v197
	v_mov_b32_e32 v187, v197
	s_nop 1
	v_permlane32_swap_b32_e32 v160, v187
	v_cndmask_b32_e64 v231, v160, v187, s[8:9]
	v_mov_b32_e32 v160, v190
	v_mov_b32_e32 v187, v190
	s_nop 1
	v_permlane32_swap_b32_e32 v160, v187
	v_cndmask_b32_e64 v198, v160, v187, s[8:9]
	v_mov_b32_e32 v160, v194
	v_mov_b32_e32 v187, v194
	s_nop 1
	v_permlane32_swap_b32_e32 v160, v187
	v_cndmask_b32_e64 v188, v160, v187, s[8:9]
	v_mov_b32_e32 v160, v191
	v_mov_b32_e32 v187, v191
	s_nop 1
	v_permlane32_swap_b32_e32 v160, v187
	v_cndmask_b32_e64 v199, v160, v187, s[8:9]
	v_mov_b32_e32 v160, v195
	v_mov_b32_e32 v187, v195
	s_nop 1
	v_permlane32_swap_b32_e32 v160, v187
	v_cndmask_b32_e64 v189, v160, v187, s[8:9]
	s_waitcnt vmcnt(2)
	v_pk_mul_f32 v[148:149], v[148:149], v[230:231]
	s_waitcnt vmcnt(1)
	v_pk_mul_f32 v[156:157], v[156:157], v[228:229]
	s_and_saveexec_b64 s[6:7], s[10:11]
	s_xor_b64 s[6:7], exec, s[6:7]
	v_pk_mul_f32 v[158:159], v[158:159], v[198:199]
	v_pk_mul_f32 v[150:151], v[150:151], v[188:189]
	v_pk_fma_f32 v[190:191], v[190:191], v[154:155], v[158:159]
	v_pk_fma_f32 v[192:193], v[192:193], v[152:153], v[156:157]
	v_pk_fma_f32 v[194:195], v[194:195], v[146:147], v[150:151]
	v_pk_fma_f32 v[196:197], v[196:197], v[144:145], v[148:149]
	s_andn2_saveexec_b64 s[6:7], s[6:7]
	v_pk_mul_f32 v[158:159], v[158:159], v[198:199]
	v_pk_mul_f32 v[150:151], v[150:151], v[188:189]
	v_pk_fma_f32 v[190:191], v[190:191], v[154:155], v[158:159] neg_lo:[0,0,1] neg_hi:[0,0,1]
	v_pk_fma_f32 v[192:193], v[192:193], v[152:153], v[156:157] neg_lo:[0,0,1] neg_hi:[0,0,1]
	v_pk_fma_f32 v[194:195], v[194:195], v[146:147], v[150:151] neg_lo:[0,0,1] neg_hi:[0,0,1]
	v_pk_fma_f32 v[196:197], v[196:197], v[144:145], v[148:149] neg_lo:[0,0,1] neg_hi:[0,0,1]
	s_or_b64 exec, exec, s[6:7]
.LBB0_291:
	v_add_u32_e32 v144, s26, v223
	v_ashrrev_i32_e32 v145, 31, v144
	v_lshlrev_b64 v[144:145], s27, v[144:145]
	v_lshl_add_u64 v[188:189], v[144:145], 1, v[184:185]
	v_cvt_pk_bf16_f32 v248, v192, v193
	v_cvt_pk_bf16_f32 v249, v190, v191
	v_cvt_pk_bf16_f32 v250, v196, v197
	v_cvt_pk_bf16_f32 v251, v194, v195
	v_mov_b64_e32 v[252:253], v[188:189]
	v_mov_b32_e32 v187, v186
	v_pk_mul_f32 v[148:149], v[36:37], v[186:187]
	v_mov_b32_e32 v144, v186
	v_mov_b32_e32 v145, v186
	v_pk_mul_f32 v[146:147], v[38:39], v[144:145]
	v_pk_mul_f32 v[144:145], v[30:31], v[144:145]
	v_pk_mul_f32 v[190:191], v[134:135], v[146:147]
	v_pk_mul_f32 v[146:147], v[28:29], v[186:187]
	v_pk_mul_f32 v[192:193], v[132:133], v[148:149]
	v_pk_mul_f32 v[186:187], v[130:131], v[144:145]
	s_and_b64 vcc, exec, s[16:17]
	v_pk_mul_f32 v[194:195], v[128:129], v[146:147]
	s_cbranch_vccnz .Lqk_st_10
	global_load_dwordx4 v[144:147], v[176:177], off offset:1040
	global_load_dwordx4 v[152:155], v[176:177], off offset:1024
	global_load_dwordx4 v[148:151], v[178:179], off offset:1040
	global_load_dwordx4 v[156:159], v[178:179], off offset:1024
	global_store_dwordx4 v[252:253], v[248:251], off
	v_mov_b32_e32 v160, v192
	v_mov_b32_e32 v196, v192
	s_nop 1
	v_permlane32_swap_b32_e32 v160, v196
	v_cndmask_b32_e64 v228, v160, v196, s[8:9]
	v_mov_b32_e32 v160, v194
	v_mov_b32_e32 v196, v194
	s_nop 1
	v_permlane32_swap_b32_e32 v160, v196
	v_cndmask_b32_e64 v230, v160, v196, s[8:9]
	v_mov_b32_e32 v160, v193
	v_mov_b32_e32 v196, v193
	s_nop 1
	v_permlane32_swap_b32_e32 v160, v196
	v_cndmask_b32_e64 v229, v160, v196, s[8:9]
	v_mov_b32_e32 v160, v195
	v_mov_b32_e32 v196, v195
	s_nop 1
	v_permlane32_swap_b32_e32 v160, v196
	v_cndmask_b32_e64 v231, v160, v196, s[8:9]
	v_mov_b32_e32 v160, v190
	v_mov_b32_e32 v196, v190
	s_nop 1
	v_permlane32_swap_b32_e32 v160, v196
	v_cndmask_b32_e64 v198, v160, v196, s[8:9]
	v_mov_b32_e32 v160, v186
	v_mov_b32_e32 v196, v186
	s_nop 1
	v_permlane32_swap_b32_e32 v160, v196
	v_cndmask_b32_e64 v196, v160, v196, s[8:9]
	v_mov_b32_e32 v160, v191
	v_mov_b32_e32 v197, v191
	s_nop 1
	v_permlane32_swap_b32_e32 v160, v197
	v_cndmask_b32_e64 v199, v160, v197, s[8:9]
	v_mov_b32_e32 v160, v187
	v_mov_b32_e32 v197, v187
	s_nop 1
	v_permlane32_swap_b32_e32 v160, v197
	v_cndmask_b32_e64 v197, v160, v197, s[8:9]
	s_waitcnt vmcnt(2)
	v_pk_mul_f32 v[148:149], v[148:149], v[230:231]
	s_waitcnt vmcnt(1)
	v_pk_mul_f32 v[156:157], v[156:157], v[228:229]
	s_and_saveexec_b64 s[6:7], s[10:11]
	s_xor_b64 s[6:7], exec, s[6:7]
	v_pk_mul_f32 v[158:159], v[158:159], v[198:199]
	v_pk_mul_f32 v[150:151], v[150:151], v[196:197]
	v_pk_fma_f32 v[190:191], v[190:191], v[154:155], v[158:159]
	v_pk_fma_f32 v[192:193], v[192:193], v[152:153], v[156:157]
	v_pk_fma_f32 v[186:187], v[186:187], v[146:147], v[150:151]
	v_pk_fma_f32 v[194:195], v[194:195], v[144:145], v[148:149]
	s_andn2_saveexec_b64 s[6:7], s[6:7]
	v_pk_mul_f32 v[158:159], v[158:159], v[198:199]
	v_pk_mul_f32 v[150:151], v[150:151], v[196:197]
	v_pk_fma_f32 v[190:191], v[190:191], v[154:155], v[158:159] neg_lo:[0,0,1] neg_hi:[0,0,1]
	v_pk_fma_f32 v[192:193], v[192:193], v[152:153], v[156:157] neg_lo:[0,0,1] neg_hi:[0,0,1]
	v_pk_fma_f32 v[186:187], v[186:187], v[146:147], v[150:151] neg_lo:[0,0,1] neg_hi:[0,0,1]
	v_pk_fma_f32 v[194:195], v[194:195], v[144:145], v[148:149] neg_lo:[0,0,1] neg_hi:[0,0,1]
	s_or_b64 exec, exec, s[6:7]
; __device__ __forceinline__ unsigned pk2(float lo, float hi) { return pg8::cvt_pk_bf16(lo, hi); }
;     __device__ __forceinline__ void operator()(const f32x4 (&acc)[2][2][4][2], const pg8::Unit& u, int wr, int wc, int fr, int fq) const {
;     ...
;                 for (int m = 0; m < 4; ++m) {
;                     const int rl = ai * 128 + wr * 64 + m * 16 + fr;
;                     const int row = pm * 256 + rl;
;                     float ss = 0.f;
; #pragma unroll
;                     for (int bj = 0; bj < 2; ++bj)
; #pragma unroll
;                         for (int n = 0; n < 2; ++n) { const f32x4 v = acc[ai][bj][m][n]; ss += (v[0] * v[0] + v[1] * v[1]) + (v[2] * v[2] + v[3] * v[3]); }
;                     ss = sum_fq(ss);
;                     const float rstd = __builtin_amdgcn_rsqf(ss * (1.0f / 64.0f) + EPS);
;                     const int sp = seq0 + rl;
; #pragma unroll
;                     for (int bj = 0; bj < 2; ++bj) {
;                         f32x4 y0 = acc[ai][bj][m][0] * (rstd * qscale) * gv[bj][0], y1 = acc[ai][bj][m][1] * (rstd * qscale) * gv[bj][1];
;                         if (!isctx) {
;                             const int pos = bj == 0 ? (sp >> 6) : (sp & 63);
;                             const f32x4 c0 = *(const f32x4*)(ropec + pos * 16 + fbase), c1 = *(const f32x4*)(ropec + pos * 16 + fbase + 4);
;                             const f32x4 s0 = *(const f32x4*)(ropes + pos * 16 + fbase), s1 = *(const f32x4*)(ropes + pos * 16 + fbase + 4);
;                             f32x4 p0, p1;
; #pragma unroll
;                             for (int j = 0; j < 4; ++j) { p0[j] = xor32(y0[j], lowhalf); p1[j] = xor32(y1[j], lowhalf); }
;                             if (lowhalf) { y0 = y0 * c0 - p0 * s0; y1 = y1 * c1 - p1 * s1; }
;                             else         { y0 = p0 * s0 + y0 * c0; y1 = p1 * s1 + y1 * c1; }
;                         }
;                         u32x4 w; w.x = pk2(y0[0], y0[1]); w.y = pk2(y0[2], y0[3]); w.z = pk2(y1[0], y1[1]); w.w = pk2(y1[2], y1[3]);
;                         *(u32x4*)(dst + (size_t)row * pitch + hcol + 32 * bj + 8 * fq) = w;
.LBB0_297:
	v_cvt_pk_bf16_f32 v248, v192, v193
	v_cvt_pk_bf16_f32 v249, v190, v191
	v_cvt_pk_bf16_f32 v250, v194, v195
	v_cvt_pk_bf16_f32 v251, v186, v187
	v_mov_b64_e32 v[252:253], v[188:189]
	s_and_b64 vcc, exec, s[16:17]
	s_nop 0
	v_mul_f32_e32 v144, v33, v33
	v_mul_f32_e32 v145, v35, v35
	v_fmac_f32_e32 v144, v32, v32
	v_fmac_f32_e32 v145, v34, v34
	v_add_f32_e32 v144, v144, v145
	v_mul_f32_e32 v145, v25, v25
	v_mul_f32_e32 v146, v27, v27
	v_fmac_f32_e32 v145, v24, v24
	v_fmac_f32_e32 v146, v26, v26
	v_add_f32_e32 v145, v145, v146
	v_add_f32_e32 v144, v144, v145
	v_mul_f32_e32 v145, v21, v21
	v_mul_f32_e32 v146, v23, v23
	v_fmac_f32_e32 v145, v20, v20
	v_fmac_f32_e32 v146, v22, v22
	v_add_f32_e32 v145, v145, v146
	v_add_f32_e32 v144, v144, v145
	v_mul_f32_e32 v145, v13, v13
	v_mul_f32_e32 v146, v15, v15
	v_fmac_f32_e32 v145, v12, v12
	v_fmac_f32_e32 v146, v14, v14
	v_add_f32_e32 v145, v145, v146
	v_add_f32_e32 v144, v144, v145
	v_mov_b32_e32 v145, v144
	s_nop 1
	v_permlane16_swap_b32_e32 v144, v145
	v_add_f32_e32 v144, v144, v145
	v_mov_b32_e32 v145, v144
	s_nop 1
	v_permlane32_swap_b32_e32 v144, v145
	v_add_f32_e32 v144, v144, v145
	v_fmamk_f32 v144, v144, 0x3c800000, v200
	v_rsq_f32_e32 v144, v144
	s_nop 0
	v_mul_f32_e32 v186, v227, v144
	v_pk_mul_f32 v[144:145], v[32:33], v[186:187] op_sel_hi:[1,0]
	v_pk_mul_f32 v[146:147], v[34:35], v[186:187] op_sel_hi:[1,0]
	v_pk_mul_f32 v[192:193], v[140:141], v[144:145]
	v_pk_mul_f32 v[190:191], v[142:143], v[146:147]
	v_pk_mul_f32 v[144:145], v[24:25], v[186:187] op_sel_hi:[1,0]
	v_pk_mul_f32 v[146:147], v[26:27], v[186:187] op_sel_hi:[1,0]
	v_pk_mul_f32 v[196:197], v[136:137], v[144:145]
	v_pk_mul_f32 v[194:195], v[138:139], v[146:147]
	s_cbranch_vccnz .Lqk_st_11
	v_add_u32_e32 v144, s5, v224
	v_ashrrev_i32_e32 v144, 2, v144
	v_and_b32_e32 v144, -16, v144
	v_ashrrev_i32_e32 v145, 31, v144
	v_lshlrev_b64 v[148:149], 2, v[144:145]
	v_lshl_add_u64 v[150:151], v[172:173], 0, v[148:149]
	v_lshl_add_u64 v[156:157], v[174:175], 0, v[148:149]
	global_load_dwordx4 v[144:147], v[150:151], off offset:16
	global_load_dwordx4 v[152:155], v[150:151], off
	s_nop 0
	global_load_dwordx4 v[148:151], v[156:157], off offset:16
	s_nop 0
	global_load_dwordx4 v[156:159], v[156:157], off
	global_store_dwordx4 v[252:253], v[248:251], off offset:64
	v_mov_b32_e32 v160, v192
	v_mov_b32_e32 v187, v192
	s_nop 1
	v_permlane32_swap_b32_e32 v160, v187
	v_cndmask_b32_e64 v228, v160, v187, s[8:9]
	v_mov_b32_e32 v160, v196
	v_mov_b32_e32 v187, v196
	s_nop 1
	v_permlane32_swap_b32_e32 v160, v187
	v_cndmask_b32_e64 v230, v160, v187, s[8:9]
	v_mov_b32_e32 v160, v193
	v_mov_b32_e32 v187, v193
	s_nop 1
	v_permlane32_swap_b32_e32 v160, v187
	v_cndmask_b32_e64 v229, v160, v187, s[8:9]
	v_mov_b32_e32 v160, v197
	v_mov_b32_e32 v187, v197
	s_nop 1
	v_permlane32_swap_b32_e32 v160, v187
	v_cndmask_b32_e64 v231, v160, v187, s[8:9]
	v_mov_b32_e32 v160, v190
	v_mov_b32_e32 v187, v190
	s_nop 1
	v_permlane32_swap_b32_e32 v160, v187
	v_cndmask_b32_e64 v198, v160, v187, s[8:9]
	v_mov_b32_e32 v160, v194
	v_mov_b32_e32 v187, v194
	s_nop 1
	v_permlane32_swap_b32_e32 v160, v187
	v_cndmask_b32_e64 v188, v160, v187, s[8:9]
	v_mov_b32_e32 v160, v191
	v_mov_b32_e32 v187, v191
	s_nop 1
	v_permlane32_swap_b32_e32 v160, v187
	v_cndmask_b32_e64 v199, v160, v187, s[8:9]
	v_mov_b32_e32 v160, v195
	v_mov_b32_e32 v187, v195
	s_nop 1
	v_permlane32_swap_b32_e32 v160, v187
	v_cndmask_b32_e64 v189, v160, v187, s[8:9]
	s_waitcnt vmcnt(2)
	v_pk_mul_f32 v[148:149], v[148:149], v[230:231]
	s_waitcnt vmcnt(1)
	v_pk_mul_f32 v[156:157], v[156:157], v[228:229]
	s_and_saveexec_b64 s[6:7], s[10:11]
	s_xor_b64 s[6:7], exec, s[6:7]
	v_pk_mul_f32 v[158:159], v[158:159], v[198:199]
	v_pk_mul_f32 v[150:151], v[150:151], v[188:189]
	v_pk_fma_f32 v[190:191], v[190:191], v[154:155], v[158:159]
	v_pk_fma_f32 v[192:193], v[192:193], v[152:153], v[156:157]
	v_pk_fma_f32 v[194:195], v[194:195], v[146:147], v[150:151]
	v_pk_fma_f32 v[196:197], v[196:197], v[144:145], v[148:149]
	s_andn2_saveexec_b64 s[6:7], s[6:7]
	v_pk_mul_f32 v[158:159], v[158:159], v[198:199]
	v_pk_mul_f32 v[150:151], v[150:151], v[188:189]
	v_pk_fma_f32 v[190:191], v[190:191], v[154:155], v[158:159] neg_lo:[0,0,1] neg_hi:[0,0,1]
	v_pk_fma_f32 v[192:193], v[192:193], v[152:153], v[156:157] neg_lo:[0,0,1] neg_hi:[0,0,1]
	v_pk_fma_f32 v[194:195], v[194:195], v[146:147], v[150:151] neg_lo:[0,0,1] neg_hi:[0,0,1]
	v_pk_fma_f32 v[196:197], v[196:197], v[144:145], v[148:149] neg_lo:[0,0,1] neg_hi:[0,0,1]
	s_or_b64 exec, exec, s[6:7]
; __device__ __forceinline__ unsigned pk2(float lo, float hi) { return pg8::cvt_pk_bf16(lo, hi); }
;     __device__ __forceinline__ void operator()(const f32x4 (&acc)[2][2][4][2], const pg8::Unit& u, int wr, int wc, int fr, int fq) const {
;     ...
;                     const int sp = seq0 + rl;
; #pragma unroll
;                     for (int bj = 0; bj < 2; ++bj) {
;                         f32x4 y0 = acc[ai][bj][m][0] * (rstd * qscale) * gv[bj][0], y1 = acc[ai][bj][m][1] * (rstd * qscale) * gv[bj][1];
;                         if (!isctx) {
;                             const int pos = bj == 0 ? (sp >> 6) : (sp & 63);
;                             const f32x4 c0 = *(const f32x4*)(ropec + pos * 16 + fbase), c1 = *(const f32x4*)(ropec + pos * 16 + fbase + 4);
;                             const f32x4 s0 = *(const f32x4*)(ropes + pos * 16 + fbase), s1 = *(const f32x4*)(ropes + pos * 16 + fbase + 4);
;                             f32x4 p0, p1;
; #pragma unroll
;                             for (int j = 0; j < 4; ++j) { p0[j] = xor32(y0[j], lowhalf); p1[j] = xor32(y1[j], lowhalf); }
;                             if (lowhalf) { y0 = y0 * c0 - p0 * s0; y1 = y1 * c1 - p1 * s1; }
;                             else         { y0 = p0 * s0 + y0 * c0; y1 = p1 * s1 + y1 * c1; }
;                         }
;                         u32x4 w; w.x = pk2(y0[0], y0[1]); w.y = pk2(y0[2], y0[3]); w.z = pk2(y1[0], y1[1]); w.w = pk2(y1[2], y1[3]);
;                         *(u32x4*)(dst + (size_t)row * pitch + hcol + 32 * bj + 8 * fq) = w;
.LBB0_303:
	v_add_u32_e32 v144, s26, v224
	v_ashrrev_i32_e32 v145, 31, v144
	v_lshlrev_b64 v[144:145], s27, v[144:145]
	v_lshl_add_u64 v[188:189], v[144:145], 1, v[184:185]
	v_cvt_pk_bf16_f32 v248, v192, v193
	v_cvt_pk_bf16_f32 v249, v190, v191
	v_cvt_pk_bf16_f32 v250, v196, v197
	v_cvt_pk_bf16_f32 v251, v194, v195
	v_mov_b64_e32 v[252:253], v[188:189]
	v_mov_b32_e32 v187, v186
	v_pk_mul_f32 v[148:149], v[20:21], v[186:187]
	v_mov_b32_e32 v144, v186
	v_mov_b32_e32 v145, v186
	v_pk_mul_f32 v[146:147], v[22:23], v[144:145]
	v_pk_mul_f32 v[144:145], v[14:15], v[144:145]
	v_pk_mul_f32 v[190:191], v[134:135], v[146:147]
	v_pk_mul_f32 v[146:147], v[12:13], v[186:187]
	v_pk_mul_f32 v[192:193], v[132:133], v[148:149]
	v_pk_mul_f32 v[186:187], v[130:131], v[144:145]
	s_and_b64 vcc, exec, s[16:17]
	v_pk_mul_f32 v[194:195], v[128:129], v[146:147]
	s_cbranch_vccnz .Lqk_st_12
	global_load_dwordx4 v[144:147], v[176:177], off offset:2064
	global_load_dwordx4 v[152:155], v[176:177], off offset:2048
	global_load_dwordx4 v[148:151], v[178:179], off offset:2064
	global_load_dwordx4 v[156:159], v[178:179], off offset:2048
	global_store_dwordx4 v[252:253], v[248:251], off
	v_mov_b32_e32 v160, v192
	v_mov_b32_e32 v196, v192
	s_nop 1
	v_permlane32_swap_b32_e32 v160, v196
	v_cndmask_b32_e64 v228, v160, v196, s[8:9]
	v_mov_b32_e32 v160, v194
	v_mov_b32_e32 v196, v194
	s_nop 1
	v_permlane32_swap_b32_e32 v160, v196
	v_cndmask_b32_e64 v230, v160, v196, s[8:9]
	v_mov_b32_e32 v160, v193
	v_mov_b32_e32 v196, v193
	s_nop 1
	v_permlane32_swap_b32_e32 v160, v196
	v_cndmask_b32_e64 v229, v160, v196, s[8:9]
	v_mov_b32_e32 v160, v195
	v_mov_b32_e32 v196, v195
	s_nop 1
	v_permlane32_swap_b32_e32 v160, v196
	v_cndmask_b32_e64 v231, v160, v196, s[8:9]
	v_mov_b32_e32 v160, v190
	v_mov_b32_e32 v196, v190
	s_nop 1
	v_permlane32_swap_b32_e32 v160, v196
	v_cndmask_b32_e64 v198, v160, v196, s[8:9]
	v_mov_b32_e32 v160, v186
	v_mov_b32_e32 v196, v186
	s_nop 1
	v_permlane32_swap_b32_e32 v160, v196
	v_cndmask_b32_e64 v196, v160, v196, s[8:9]
	v_mov_b32_e32 v160, v191
	v_mov_b32_e32 v197, v191
	s_nop 1
	v_permlane32_swap_b32_e32 v160, v197
	v_cndmask_b32_e64 v199, v160, v197, s[8:9]
	v_mov_b32_e32 v160, v187
	v_mov_b32_e32 v197, v187
	s_nop 1
	v_permlane32_swap_b32_e32 v160, v197
	v_cndmask_b32_e64 v197, v160, v197, s[8:9]
	s_waitcnt vmcnt(2)
	v_pk_mul_f32 v[148:149], v[148:149], v[230:231]
	s_waitcnt vmcnt(1)
	v_pk_mul_f32 v[156:157], v[156:157], v[228:229]
	s_and_saveexec_b64 s[6:7], s[10:11]
	s_xor_b64 s[6:7], exec, s[6:7]
	v_pk_mul_f32 v[158:159], v[158:159], v[198:199]
	v_pk_mul_f32 v[150:151], v[150:151], v[196:197]
	v_pk_fma_f32 v[190:191], v[190:191], v[154:155], v[158:159]
	v_pk_fma_f32 v[192:193], v[192:193], v[152:153], v[156:157]
	v_pk_fma_f32 v[186:187], v[186:187], v[146:147], v[150:151]
	v_pk_fma_f32 v[194:195], v[194:195], v[144:145], v[148:149]
	s_andn2_saveexec_b64 s[6:7], s[6:7]
	v_pk_mul_f32 v[158:159], v[158:159], v[198:199]
	v_pk_mul_f32 v[150:151], v[150:151], v[196:197]
	v_pk_fma_f32 v[190:191], v[190:191], v[154:155], v[158:159] neg_lo:[0,0,1] neg_hi:[0,0,1]
	v_pk_fma_f32 v[192:193], v[192:193], v[152:153], v[156:157] neg_lo:[0,0,1] neg_hi:[0,0,1]
	v_pk_fma_f32 v[186:187], v[186:187], v[146:147], v[150:151] neg_lo:[0,0,1] neg_hi:[0,0,1]
	v_pk_fma_f32 v[194:195], v[194:195], v[144:145], v[148:149] neg_lo:[0,0,1] neg_hi:[0,0,1]
	s_or_b64 exec, exec, s[6:7]
; __device__ __forceinline__ unsigned pk2(float lo, float hi) { return pg8::cvt_pk_bf16(lo, hi); }
;     __device__ __forceinline__ void operator()(const f32x4 (&acc)[2][2][4][2], const pg8::Unit& u, int wr, int wc, int fr, int fq) const {
;     ...
;                 for (int m = 0; m < 4; ++m) {
;                     const int rl = ai * 128 + wr * 64 + m * 16 + fr;
;                     const int row = pm * 256 + rl;
;                     float ss = 0.f;
; #pragma unroll
;                     for (int bj = 0; bj < 2; ++bj)
; #pragma unroll
;                         for (int n = 0; n < 2; ++n) { const f32x4 v = acc[ai][bj][m][n]; ss += (v[0] * v[0] + v[1] * v[1]) + (v[2] * v[2] + v[3] * v[3]); }
;                     ss = sum_fq(ss);
;                     const float rstd = __builtin_amdgcn_rsqf(ss * (1.0f / 64.0f) + EPS);
;                     const int sp = seq0 + rl;
; #pragma unroll
;                     for (int bj = 0; bj < 2; ++bj) {
;                         f32x4 y0 = acc[ai][bj][m][0] * (rstd * qscale) * gv[bj][0], y1 = acc[ai][bj][m][1] * (rstd * qscale) * gv[bj][1];
;                         if (!isctx) {
;                             const int pos = bj == 0 ? (sp >> 6) : (sp & 63);
;                             const f32x4 c0 = *(const f32x4*)(ropec + pos * 16 + fbase), c1 = *(const f32x4*)(ropec + pos * 16 + fbase + 4);
;                             const f32x4 s0 = *(const f32x4*)(ropes + pos * 16 + fbase), s1 = *(const f32x4*)(ropes + pos * 16 + fbase + 4);
;                             f32x4 p0, p1;
; #pragma unroll
;                             for (int j = 0; j < 4; ++j) { p0[j] = xor32(y0[j], lowhalf); p1[j] = xor32(y1[j], lowhalf); }
;                             if (lowhalf) { y0 = y0 * c0 - p0 * s0; y1 = y1 * c1 - p1 * s1; }
;                             else         { y0 = p0 * s0 + y0 * c0; y1 = p1 * s1 + y1 * c1; }
;                         }
;                         u32x4 w; w.x = pk2(y0[0], y0[1]); w.y = pk2(y0[2], y0[3]); w.z = pk2(y1[0], y1[1]); w.w = pk2(y1[2], y1[3]);
;                         *(u32x4*)(dst + (size_t)row * pitch + hcol + 32 * bj + 8 * fq) = w;
.LBB0_309:
	v_cvt_pk_bf16_f32 v248, v192, v193
	v_cvt_pk_bf16_f32 v249, v190, v191
	v_cvt_pk_bf16_f32 v250, v194, v195
	v_cvt_pk_bf16_f32 v251, v186, v187
	v_mov_b64_e32 v[252:253], v[188:189]
	s_and_b64 vcc, exec, s[16:17]
	s_nop 0
	v_mul_f32_e32 v144, v17, v17
	v_mul_f32_e32 v145, v19, v19
	v_fmac_f32_e32 v144, v16, v16
	v_fmac_f32_e32 v145, v18, v18
	v_add_f32_e32 v144, v144, v145
	v_mul_f32_e32 v145, v9, v9
	v_mul_f32_e32 v146, v11, v11
	v_fmac_f32_e32 v145, v8, v8
	v_fmac_f32_e32 v146, v10, v10
	v_add_f32_e32 v145, v145, v146
	v_add_f32_e32 v144, v144, v145
	v_mul_f32_e32 v145, v5, v5
	v_mul_f32_e32 v146, v7, v7
	v_fmac_f32_e32 v145, v4, v4
	v_fmac_f32_e32 v146, v6, v6
	v_add_f32_e32 v145, v145, v146
	v_add_f32_e32 v144, v144, v145
	v_mul_f32_e32 v145, v1, v1
	v_mul_f32_e32 v146, v3, v3
	v_fmac_f32_e32 v145, v0, v0
	v_fmac_f32_e32 v146, v2, v2
	v_add_f32_e32 v145, v145, v146
	v_add_f32_e32 v144, v144, v145
	v_mov_b32_e32 v145, v144
	s_nop 1
	v_permlane16_swap_b32_e32 v144, v145
	v_add_f32_e32 v144, v144, v145
	v_mov_b32_e32 v145, v144
	s_nop 1
	v_permlane32_swap_b32_e32 v144, v145
	v_add_f32_e32 v144, v144, v145
	v_fmamk_f32 v144, v144, 0x3c800000, v200
	v_rsq_f32_e32 v144, v144
	s_nop 0
	v_mul_f32_e32 v152, v227, v144
	v_pk_mul_f32 v[144:145], v[16:17], v[152:153] op_sel_hi:[1,0]
	v_pk_mul_f32 v[146:147], v[18:19], v[152:153] op_sel_hi:[1,0]
	v_pk_mul_f32 v[156:157], v[140:141], v[144:145]
	v_pk_mul_f32 v[154:155], v[142:143], v[146:147]
	v_pk_mul_f32 v[140:141], v[8:9], v[152:153] op_sel_hi:[1,0]
	v_pk_mul_f32 v[142:143], v[10:11], v[152:153] op_sel_hi:[1,0]
	v_pk_mul_f32 v[186:187], v[136:137], v[140:141]
	v_pk_mul_f32 v[158:159], v[138:139], v[142:143]
	s_cbranch_vccnz .Lqk_st_13
	v_add_u32_e32 v136, s5, v225
	v_ashrrev_i32_e32 v136, 2, v136
	v_and_b32_e32 v136, -16, v136
	v_ashrrev_i32_e32 v137, 31, v136
	v_lshlrev_b64 v[140:141], 2, v[136:137]
	v_lshl_add_u64 v[142:143], v[172:173], 0, v[140:141]
	v_lshl_add_u64 v[148:149], v[174:175], 0, v[140:141]
	global_load_dwordx4 v[136:139], v[142:143], off offset:16
	global_load_dwordx4 v[144:147], v[142:143], off
	s_nop 0
	global_load_dwordx4 v[140:143], v[148:149], off offset:16
	s_nop 0
	global_load_dwordx4 v[148:151], v[148:149], off
	global_store_dwordx4 v[252:253], v[248:251], off offset:64
	v_mov_b32_e32 v153, v156
	v_mov_b32_e32 v160, v156
	s_nop 1
	v_permlane32_swap_b32_e32 v153, v160
	v_cndmask_b32_e64 v192, v153, v160, s[8:9]
	v_mov_b32_e32 v153, v186
	v_mov_b32_e32 v160, v186
	s_nop 1
	v_permlane32_swap_b32_e32 v153, v160
	v_cndmask_b32_e64 v194, v153, v160, s[8:9]
	v_mov_b32_e32 v153, v157
	v_mov_b32_e32 v160, v157
	s_nop 1
	v_permlane32_swap_b32_e32 v153, v160
	v_cndmask_b32_e64 v193, v153, v160, s[8:9]
	v_mov_b32_e32 v153, v187
	v_mov_b32_e32 v160, v187
	s_nop 1
	v_permlane32_swap_b32_e32 v153, v160
	v_cndmask_b32_e64 v195, v153, v160, s[8:9]
	v_mov_b32_e32 v153, v154
	v_mov_b32_e32 v160, v154
	s_nop 1
	v_permlane32_swap_b32_e32 v153, v160
	v_cndmask_b32_e64 v190, v153, v160, s[8:9]
	v_mov_b32_e32 v153, v158
	v_mov_b32_e32 v160, v158
	s_nop 1
	v_permlane32_swap_b32_e32 v153, v160
	v_cndmask_b32_e64 v188, v153, v160, s[8:9]
	v_mov_b32_e32 v153, v155
	v_mov_b32_e32 v160, v155
	s_nop 1
	v_permlane32_swap_b32_e32 v153, v160
	v_cndmask_b32_e64 v191, v153, v160, s[8:9]
	v_mov_b32_e32 v153, v159
	v_mov_b32_e32 v160, v159
	s_nop 1
	v_permlane32_swap_b32_e32 v153, v160
	v_cndmask_b32_e64 v189, v153, v160, s[8:9]
	s_waitcnt vmcnt(2)
	v_pk_mul_f32 v[140:141], v[140:141], v[194:195]
	s_waitcnt vmcnt(1)
	v_pk_mul_f32 v[148:149], v[148:149], v[192:193]
	s_and_saveexec_b64 s[6:7], s[10:11]
	s_xor_b64 s[6:7], exec, s[6:7]
	v_pk_mul_f32 v[150:151], v[150:151], v[190:191]
	v_pk_mul_f32 v[142:143], v[142:143], v[188:189]
	v_pk_fma_f32 v[154:155], v[154:155], v[146:147], v[150:151]
	v_pk_fma_f32 v[156:157], v[156:157], v[144:145], v[148:149]
	v_pk_fma_f32 v[158:159], v[158:159], v[138:139], v[142:143]
	v_pk_fma_f32 v[186:187], v[186:187], v[136:137], v[140:141]
	s_andn2_saveexec_b64 s[6:7], s[6:7]
	v_pk_mul_f32 v[150:151], v[150:151], v[190:191]
	v_pk_mul_f32 v[142:143], v[142:143], v[188:189]
	v_pk_fma_f32 v[154:155], v[154:155], v[146:147], v[150:151] neg_lo:[0,0,1] neg_hi:[0,0,1]
	v_pk_fma_f32 v[156:157], v[156:157], v[144:145], v[148:149] neg_lo:[0,0,1] neg_hi:[0,0,1]
	v_pk_fma_f32 v[158:159], v[158:159], v[138:139], v[142:143] neg_lo:[0,0,1] neg_hi:[0,0,1]
	v_pk_fma_f32 v[186:187], v[186:187], v[136:137], v[140:141] neg_lo:[0,0,1] neg_hi:[0,0,1]
	s_or_b64 exec, exec, s[6:7]
